# static priority: all per-block s_setprio flips removed, one s_setprio 1 for waves 4-7 at kernel entry
# baseline (speedup 1.0000x reference)
.LBB0_18:
	s_lshr_b32 s23, s24, 6
	s_cmp_ge_u32 s23, 4
	s_cbranch_scc0 .Lprio_done
	s_setprio 1
.Lprio_done:
	s_add_u32 s72, s30, 0x2f00000
	s_addc_u32 s73, s31, 0
	s_lshl_b32 s2, s80, 3
	s_lshl_b32 s74, s34, 3
	s_cmp_lt_i32 s68, 1
	s_cselect_b64 s[0:1], -1, 0
	s_cmp_gt_i32 s69, 0
	s_cselect_b64 s[4:5], -1, 0
	s_and_b64 s[6:7], s[0:1], s[4:5]
	v_writelane_b32 v255, s24, 19
	s_andn2_b64 vcc, exec, s[6:7]
	v_and_b32_e32 v222, 63, v199
	s_cbranch_vccnz .LBB0_42
	s_cmpk_lt_i32 s80, 0x90
	s_cselect_b64 s[8:9], -1, 0
	s_cmpk_gt_i32 s80, 0x8f
	s_cbranch_scc1 .LBB0_30
	v_lshlrev_b32_e32 v0, 2, v199
	v_mov_b32_e32 v1, 0
	s_movk_i32 s0, 0xf000
	v_lshl_add_u64 v[2:3], s[60:61], 0, v[0:1]
	s_mov_b32 s1, -1
	v_add_u32_e32 v6, 0, v0
	v_lshl_add_u64 v[2:3], v[2:3], 0, s[0:1]
	v_lshl_add_u64 v[4:5], s[62:63], 0, v[0:1]
	s_mov_b64 s[0:1], 0
	s_movk_i32 s3, 0x400
	s_mov_b64 s[4:5], 0x800
	s_movk_i32 s10, 0x11ff
	v_mov_b32_e32 v1, v199

.LBB0_189:
	ds_read_b128 v[156:159], v152
	ds_read_b128 v[160:163], v152 offset:1024
	ds_read_b128 v[164:167], v152 offset:2048
	ds_read_b128 v[168:171], v152 offset:3072
	ds_read_b128 v[172:175], v153
	ds_read_b128 v[176:179], v153 offset:1024
	ds_read_b128 v[180:183], v153 offset:2048
	ds_read_b128 v[184:187], v153 offset:3072
	s_add_u32 s82, s80, 0xfffc0080
	s_addc_u32 s83, s81, -1
	s_cmp_eq_u32 s96, 12
	s_cselect_b32 s85, s10, s83
	s_cselect_b32 s84, s11, s82
	s_cselect_b32 s83, s63, s95
	s_cselect_b32 s82, s65, s94
	v_lshl_add_u64 v[144:145], s[80:81], 0, v[136:137]
	s_add_i32 m0, s45, 0xc000
	ds_read_b128 v[188:191], v154
	ds_read_b128 v[192:195], v154 offset:1024
	ds_read_b128 v[200:203], v154 offset:2048
	ds_read_b128 v[204:207], v154 offset:3072
	ds_read_b128 v[208:211], v154 offset:4096
	ds_read_b128 v[212:215], v154 offset:5120
	ds_read_b128 v[216:219], v154 offset:6144
	ds_read_b128 v[224:227], v154 offset:7168
	global_load_lds_dwordx4 v[144:145], off
	v_lshl_add_u64 v[144:145], s[80:81], 0, v[138:139]
	s_add_i32 m0, s45, 0xe000
	s_nop 0
	global_load_lds_dwordx4 v[144:145], off
	s_waitcnt vmcnt(8)
	s_waitcnt lgkmcnt(0)
	s_barrier
	s_waitcnt lgkmcnt(0)
	v_mfma_f32_16x16x32_bf16 v[124:127], v[156:159], v[188:191], v[124:127]
	v_mfma_f32_16x16x32_bf16 v[120:123], v[164:167], v[188:191], v[120:123]
	v_mfma_f32_16x16x32_bf16 v[108:111], v[156:159], v[200:203], v[108:111]
	v_mfma_f32_16x16x32_bf16 v[104:107], v[164:167], v[200:203], v[104:107]
	v_mfma_f32_16x16x32_bf16 v[92:95], v[156:159], v[208:211], v[92:95]
	v_mfma_f32_16x16x32_bf16 v[88:91], v[164:167], v[208:211], v[88:91]
	v_mfma_f32_16x16x32_bf16 v[76:79], v[156:159], v[216:219], v[76:79]
	v_mfma_f32_16x16x32_bf16 v[72:75], v[164:167], v[216:219], v[72:75]
	v_mfma_f32_16x16x32_bf16 v[124:127], v[160:163], v[192:195], v[124:127]
	v_mfma_f32_16x16x32_bf16 v[120:123], v[168:171], v[192:195], v[120:123]
	v_mfma_f32_16x16x32_bf16 v[108:111], v[160:163], v[204:207], v[108:111]
	v_mfma_f32_16x16x32_bf16 v[104:107], v[168:171], v[204:207], v[104:107]
	v_mfma_f32_16x16x32_bf16 v[92:95], v[160:163], v[212:215], v[92:95]
	v_mfma_f32_16x16x32_bf16 v[88:91], v[168:171], v[212:215], v[88:91]
	v_mfma_f32_16x16x32_bf16 v[76:79], v[160:163], v[224:227], v[76:79]
	v_mfma_f32_16x16x32_bf16 v[72:75], v[168:171], v[224:227], v[72:75]
	v_mfma_f32_16x16x32_bf16 v[116:119], v[172:175], v[188:191], v[116:119]
	v_mfma_f32_16x16x32_bf16 v[112:115], v[180:183], v[188:191], v[112:115]
	v_mfma_f32_16x16x32_bf16 v[100:103], v[172:175], v[200:203], v[100:103]
	v_mfma_f32_16x16x32_bf16 v[96:99], v[180:183], v[200:203], v[96:99]
	v_mfma_f32_16x16x32_bf16 v[84:87], v[172:175], v[208:211], v[84:87]
	v_mfma_f32_16x16x32_bf16 v[80:83], v[180:183], v[208:211], v[80:83]
	v_mfma_f32_16x16x32_bf16 v[68:71], v[172:175], v[216:219], v[68:71]
	v_mfma_f32_16x16x32_bf16 v[64:67], v[180:183], v[216:219], v[64:67]
	v_mfma_f32_16x16x32_bf16 v[116:119], v[176:179], v[192:195], v[116:119]
	v_mfma_f32_16x16x32_bf16 v[112:115], v[184:187], v[192:195], v[112:115]
	v_mfma_f32_16x16x32_bf16 v[100:103], v[176:179], v[204:207], v[100:103]
	v_mfma_f32_16x16x32_bf16 v[96:99], v[184:187], v[204:207], v[96:99]
	v_mfma_f32_16x16x32_bf16 v[84:87], v[176:179], v[212:215], v[84:87]
	v_mfma_f32_16x16x32_bf16 v[80:83], v[184:187], v[212:215], v[80:83]
	v_mfma_f32_16x16x32_bf16 v[68:71], v[176:179], v[224:227], v[68:71]
	v_mfma_f32_16x16x32_bf16 v[64:67], v[184:187], v[224:227], v[64:67]
	s_barrier
	s_add_i32 s97, s90, s2
	v_lshl_add_u64 v[144:145], s[82:83], 0, v[132:133]
	s_mov_b32 m0, s97
	ds_read_b128 v[188:191], v154 offset:16384
	ds_read_b128 v[192:195], v154 offset:17408
	ds_read_b128 v[200:203], v154 offset:18432
	ds_read_b128 v[204:207], v154 offset:19456
	ds_read_b128 v[208:211], v154 offset:20480
	ds_read_b128 v[212:215], v154 offset:21504
	ds_read_b128 v[216:219], v154 offset:22528
	ds_read_b128 v[224:227], v154 offset:23552
	global_load_lds_dwordx4 v[144:145], off
	s_add_i32 m0, s97, 0x2000
	s_add_u32 vcc_lo, s82, 0x40000
	v_lshl_add_u64 v[196:197], s[82:83], 0, v[128:129]
	s_addc_u32 vcc_hi, s83, 0
	s_add_i32 s97, s91, s2
	global_load_lds_dwordx4 v[196:197], off
	v_lshl_add_u64 v[220:221], vcc, 0, v[132:133]
	s_mov_b32 m0, s97
	v_lshl_add_u64 v[228:229], s[84:85], 0, v[130:131]
	global_load_lds_dwordx4 v[220:221], off
	v_lshl_add_u64 v[220:221], vcc, 0, v[128:129]
	s_add_i32 m0, s97, 0x2000
	s_nop 0
	global_load_lds_dwordx4 v[220:221], off
	v_lshl_add_u64 v[220:221], s[84:85], 0, v[134:135]
	s_mov_b32 m0, s45
	s_nop 0
	global_load_lds_dwordx4 v[220:221], off
	s_mov_b32 m0, s70
	s_nop 0
	global_load_lds_dwordx4 v[228:229], off
	s_waitcnt vmcnt(8)
	s_waitcnt lgkmcnt(0)
	s_barrier
	s_waitcnt lgkmcnt(0)
	v_mfma_f32_16x16x32_bf16 v[60:63], v[156:159], v[188:191], v[60:63]
	v_mfma_f32_16x16x32_bf16 v[56:59], v[164:167], v[188:191], v[56:59]
	v_mfma_f32_16x16x32_bf16 v[44:47], v[156:159], v[200:203], v[44:47]
	v_mfma_f32_16x16x32_bf16 v[40:43], v[164:167], v[200:203], v[40:43]
	v_mfma_f32_16x16x32_bf16 v[28:31], v[156:159], v[208:211], v[28:31]
	v_mfma_f32_16x16x32_bf16 v[24:27], v[164:167], v[208:211], v[24:27]
	v_mfma_f32_16x16x32_bf16 v[12:15], v[156:159], v[216:219], v[12:15]
	v_mfma_f32_16x16x32_bf16 v[8:11], v[164:167], v[216:219], v[8:11]
	v_mfma_f32_16x16x32_bf16 v[60:63], v[160:163], v[192:195], v[60:63]
	v_mfma_f32_16x16x32_bf16 v[56:59], v[168:171], v[192:195], v[56:59]
	v_mfma_f32_16x16x32_bf16 v[44:47], v[160:163], v[204:207], v[44:47]
	v_mfma_f32_16x16x32_bf16 v[40:43], v[168:171], v[204:207], v[40:43]
	v_mfma_f32_16x16x32_bf16 v[28:31], v[160:163], v[212:215], v[28:31]
	v_mfma_f32_16x16x32_bf16 v[24:27], v[168:171], v[212:215], v[24:27]
	v_mfma_f32_16x16x32_bf16 v[12:15], v[160:163], v[224:227], v[12:15]
	v_mfma_f32_16x16x32_bf16 v[8:11], v[168:171], v[224:227], v[8:11]
	v_mfma_f32_16x16x32_bf16 v[52:55], v[172:175], v[188:191], v[52:55]
	v_mfma_f32_16x16x32_bf16 v[48:51], v[180:183], v[188:191], v[48:51]
	v_mfma_f32_16x16x32_bf16 v[36:39], v[172:175], v[200:203], v[36:39]
	v_mfma_f32_16x16x32_bf16 v[32:35], v[180:183], v[200:203], v[32:35]
	v_mfma_f32_16x16x32_bf16 v[20:23], v[172:175], v[208:211], v[20:23]
	v_mfma_f32_16x16x32_bf16 v[16:19], v[180:183], v[208:211], v[16:19]
	v_mfma_f32_16x16x32_bf16 v[4:7], v[172:175], v[216:219], v[4:7]
	v_mfma_f32_16x16x32_bf16 v[0:3], v[180:183], v[216:219], v[0:3]
	v_mfma_f32_16x16x32_bf16 v[52:55], v[176:179], v[192:195], v[52:55]
	v_mfma_f32_16x16x32_bf16 v[48:51], v[184:187], v[192:195], v[48:51]
	v_mfma_f32_16x16x32_bf16 v[36:39], v[176:179], v[204:207], v[36:39]
	v_mfma_f32_16x16x32_bf16 v[32:35], v[184:187], v[204:207], v[32:35]
	v_mfma_f32_16x16x32_bf16 v[20:23], v[176:179], v[212:215], v[20:23]
	v_mfma_f32_16x16x32_bf16 v[16:19], v[184:187], v[212:215], v[16:19]
	v_mfma_f32_16x16x32_bf16 v[4:7], v[176:179], v[224:227], v[4:7]
	v_mfma_f32_16x16x32_bf16 v[0:3], v[184:187], v[224:227], v[0:3]
	s_barrier
	s_add_i32 s97, 0, 0x18000
	v_add_u32_e32 v155, s97, v147
	s_add_i32 vcc_lo, 0, 0x1c000
	ds_read_b128 v[156:159], v155
	ds_read_b128 v[160:163], v155 offset:1024
	ds_read_b128 v[164:167], v155 offset:2048
	ds_read_b128 v[168:171], v155 offset:3072
	v_add_u32_e32 v155, vcc_lo, v147
	ds_read_b128 v[172:175], v155
	ds_read_b128 v[176:179], v155 offset:1024
	ds_read_b128 v[180:183], v155 offset:2048
	ds_read_b128 v[184:187], v155 offset:3072
	s_add_u32 s84, s84, 0x40000
	s_addc_u32 s85, s85, 0
	s_mov_b32 m0, s71
	v_lshl_add_u64 v[230:231], s[84:85], 0, v[134:135]
	ds_read_b128 v[188:191], v154 offset:32768
	ds_read_b128 v[192:195], v154 offset:33792
	ds_read_b128 v[200:203], v154 offset:34816
	ds_read_b128 v[204:207], v154 offset:35840
	ds_read_b128 v[208:211], v154 offset:36864
	ds_read_b128 v[212:215], v154 offset:37888
	ds_read_b128 v[216:219], v154 offset:38912
	ds_read_b128 v[224:227], v154 offset:39936
	global_load_lds_dwordx4 v[230:231], off
	v_lshl_add_u64 v[230:231], s[84:85], 0, v[130:131]
	s_mov_b32 m0, s75
	s_nop 0
	global_load_lds_dwordx4 v[230:231], off
	s_waitcnt vmcnt(8)
	s_waitcnt lgkmcnt(0)
	s_barrier
	s_waitcnt lgkmcnt(0)
	v_mfma_f32_16x16x32_bf16 v[124:127], v[156:159], v[188:191], v[124:127]
	v_mfma_f32_16x16x32_bf16 v[120:123], v[164:167], v[188:191], v[120:123]
	v_mfma_f32_16x16x32_bf16 v[108:111], v[156:159], v[200:203], v[108:111]
	v_mfma_f32_16x16x32_bf16 v[104:107], v[164:167], v[200:203], v[104:107]
	v_mfma_f32_16x16x32_bf16 v[92:95], v[156:159], v[208:211], v[92:95]
	v_mfma_f32_16x16x32_bf16 v[88:91], v[164:167], v[208:211], v[88:91]
	v_mfma_f32_16x16x32_bf16 v[76:79], v[156:159], v[216:219], v[76:79]
	v_mfma_f32_16x16x32_bf16 v[72:75], v[164:167], v[216:219], v[72:75]
	v_mfma_f32_16x16x32_bf16 v[124:127], v[160:163], v[192:195], v[124:127]
	v_mfma_f32_16x16x32_bf16 v[120:123], v[168:171], v[192:195], v[120:123]
	v_mfma_f32_16x16x32_bf16 v[108:111], v[160:163], v[204:207], v[108:111]
	v_mfma_f32_16x16x32_bf16 v[104:107], v[168:171], v[204:207], v[104:107]
	v_mfma_f32_16x16x32_bf16 v[92:95], v[160:163], v[212:215], v[92:95]
	v_mfma_f32_16x16x32_bf16 v[88:91], v[168:171], v[212:215], v[88:91]
	v_mfma_f32_16x16x32_bf16 v[76:79], v[160:163], v[224:227], v[76:79]
	v_mfma_f32_16x16x32_bf16 v[72:75], v[168:171], v[224:227], v[72:75]
	v_mfma_f32_16x16x32_bf16 v[116:119], v[172:175], v[188:191], v[116:119]
	v_mfma_f32_16x16x32_bf16 v[112:115], v[180:183], v[188:191], v[112:115]
	v_mfma_f32_16x16x32_bf16 v[100:103], v[172:175], v[200:203], v[100:103]
	v_mfma_f32_16x16x32_bf16 v[96:99], v[180:183], v[200:203], v[96:99]
	v_mfma_f32_16x16x32_bf16 v[84:87], v[172:175], v[208:211], v[84:87]
	v_mfma_f32_16x16x32_bf16 v[80:83], v[180:183], v[208:211], v[80:83]
	v_mfma_f32_16x16x32_bf16 v[68:71], v[172:175], v[216:219], v[68:71]
	v_mfma_f32_16x16x32_bf16 v[64:67], v[180:183], v[216:219], v[64:67]
	v_mfma_f32_16x16x32_bf16 v[116:119], v[176:179], v[192:195], v[116:119]
	v_mfma_f32_16x16x32_bf16 v[112:115], v[184:187], v[192:195], v[112:115]
	v_mfma_f32_16x16x32_bf16 v[100:103], v[176:179], v[204:207], v[100:103]
	v_mfma_f32_16x16x32_bf16 v[96:99], v[184:187], v[204:207], v[96:99]
	v_mfma_f32_16x16x32_bf16 v[84:87], v[176:179], v[212:215], v[84:87]
	v_mfma_f32_16x16x32_bf16 v[80:83], v[184:187], v[212:215], v[80:83]
	v_mfma_f32_16x16x32_bf16 v[68:71], v[176:179], v[224:227], v[68:71]
	v_mfma_f32_16x16x32_bf16 v[64:67], v[184:187], v[224:227], v[64:67]
	s_barrier
	s_add_i32 s84, s97, s2
	v_lshl_add_u64 v[144:145], v[144:145], 0, s[8:9]
	s_mov_b32 m0, s84
	ds_read_b128 v[188:191], v154 offset:49152
	ds_read_b128 v[192:195], v154 offset:50176
	ds_read_b128 v[200:203], v154 offset:51200
	ds_read_b128 v[204:207], v154 offset:52224
	ds_read_b128 v[208:211], v154 offset:53248
	ds_read_b128 v[212:215], v154 offset:54272
	ds_read_b128 v[216:219], v154 offset:55296
	ds_read_b128 v[224:227], v154 offset:56320
	global_load_lds_dwordx4 v[144:145], off
	s_add_i32 m0, s84, 0x2000
	s_add_u32 s82, s82, 0x40080
	v_lshl_add_u64 v[144:145], v[196:197], 0, s[8:9]
	s_addc_u32 s83, s83, 0
	s_add_i32 s84, vcc_lo, s2
	global_load_lds_dwordx4 v[144:145], off
	v_lshl_add_u64 v[144:145], s[82:83], 0, v[132:133]
	s_mov_b32 m0, s84
	s_nop 0
	global_load_lds_dwordx4 v[144:145], off
	v_lshl_add_u64 v[144:145], s[82:83], 0, v[128:129]
	s_add_i32 m0, s84, 0x2000
	s_nop 0
	global_load_lds_dwordx4 v[144:145], off
	v_lshl_add_u64 v[144:145], v[220:221], 0, s[8:9]
	s_mov_b32 m0, s86
	s_nop 0
	global_load_lds_dwordx4 v[144:145], off
	v_lshl_add_u64 v[144:145], v[228:229], 0, s[8:9]
	s_mov_b32 m0, s87
	s_nop 0
	global_load_lds_dwordx4 v[144:145], off
	s_waitcnt vmcnt(8)
	s_waitcnt lgkmcnt(0)
	s_barrier
	s_waitcnt lgkmcnt(0)
	v_mfma_f32_16x16x32_bf16 v[60:63], v[156:159], v[188:191], v[60:63]
	v_mfma_f32_16x16x32_bf16 v[56:59], v[164:167], v[188:191], v[56:59]
	v_mfma_f32_16x16x32_bf16 v[44:47], v[156:159], v[200:203], v[44:47]
	v_mfma_f32_16x16x32_bf16 v[40:43], v[164:167], v[200:203], v[40:43]
	v_mfma_f32_16x16x32_bf16 v[28:31], v[156:159], v[208:211], v[28:31]
	v_mfma_f32_16x16x32_bf16 v[24:27], v[164:167], v[208:211], v[24:27]
	v_mfma_f32_16x16x32_bf16 v[12:15], v[156:159], v[216:219], v[12:15]
	v_mfma_f32_16x16x32_bf16 v[8:11], v[164:167], v[216:219], v[8:11]
	v_mfma_f32_16x16x32_bf16 v[60:63], v[160:163], v[192:195], v[60:63]
	v_mfma_f32_16x16x32_bf16 v[56:59], v[168:171], v[192:195], v[56:59]
	v_mfma_f32_16x16x32_bf16 v[44:47], v[160:163], v[204:207], v[44:47]
	v_mfma_f32_16x16x32_bf16 v[40:43], v[168:171], v[204:207], v[40:43]
	v_mfma_f32_16x16x32_bf16 v[28:31], v[160:163], v[212:215], v[28:31]
	v_mfma_f32_16x16x32_bf16 v[24:27], v[168:171], v[212:215], v[24:27]
	v_mfma_f32_16x16x32_bf16 v[12:15], v[160:163], v[224:227], v[12:15]
	v_mfma_f32_16x16x32_bf16 v[8:11], v[168:171], v[224:227], v[8:11]
	v_mfma_f32_16x16x32_bf16 v[52:55], v[172:175], v[188:191], v[52:55]
	v_mfma_f32_16x16x32_bf16 v[48:51], v[180:183], v[188:191], v[48:51]
	v_mfma_f32_16x16x32_bf16 v[36:39], v[172:175], v[200:203], v[36:39]
	v_mfma_f32_16x16x32_bf16 v[32:35], v[180:183], v[200:203], v[32:35]
	v_mfma_f32_16x16x32_bf16 v[20:23], v[172:175], v[208:211], v[20:23]
	v_mfma_f32_16x16x32_bf16 v[16:19], v[180:183], v[208:211], v[16:19]
	v_mfma_f32_16x16x32_bf16 v[4:7], v[172:175], v[216:219], v[4:7]
	v_mfma_f32_16x16x32_bf16 v[0:3], v[180:183], v[216:219], v[0:3]
	v_mfma_f32_16x16x32_bf16 v[52:55], v[176:179], v[192:195], v[52:55]
	v_mfma_f32_16x16x32_bf16 v[48:51], v[184:187], v[192:195], v[48:51]
	v_mfma_f32_16x16x32_bf16 v[36:39], v[176:179], v[204:207], v[36:39]
	v_mfma_f32_16x16x32_bf16 v[32:35], v[184:187], v[204:207], v[32:35]
	v_mfma_f32_16x16x32_bf16 v[20:23], v[176:179], v[212:215], v[20:23]
	v_mfma_f32_16x16x32_bf16 v[16:19], v[184:187], v[212:215], v[16:19]
	v_mfma_f32_16x16x32_bf16 v[4:7], v[176:179], v[224:227], v[4:7]
	v_mfma_f32_16x16x32_bf16 v[0:3], v[184:187], v[224:227], v[0:3]
	s_barrier
	s_add_i32 s96, s96, 2
	s_add_u32 s80, s80, 0x100
	s_addc_u32 s81, s81, 0
	s_add_u32 s94, s94, 0x100
	s_addc_u32 s95, s95, 0
	s_cmp_gt_u32 s96, 13
	s_cbranch_scc0 .LBB0_189
	s_and_b64 vcc, exec, s[60:61]
	s_cbranch_vccz .LBB0_192
	s_barrier

.LBB0_340:
	ds_read_b128 v[144:147], v171
	ds_read_b128 v[148:151], v171 offset:1024
	ds_read_b128 v[152:155], v171 offset:2048
	ds_read_b128 v[156:159], v171 offset:3072
	ds_read_b128 v[160:163], v172
	ds_read_b128 v[164:167], v172 offset:1024
	ds_read_b128 v[176:179], v172 offset:2048
	ds_read_b128 v[180:183], v172 offset:3072
	s_add_u32 s56, s54, 0xfff50080
	s_addc_u32 s57, s55, -1
	s_cmp_eq_u32 s84, 40
	s_cselect_b32 s59, s7, s57
	s_cselect_b32 s58, s6, s56
	s_cselect_b32 s57, s51, s83
	s_cselect_b32 s56, s50, s82
	v_lshl_add_u64 v[196:197], s[54:55], 0, v[136:137]
	s_add_i32 m0, s17, 0xc000
	ds_read_b128 v[184:187], v173
	ds_read_b128 v[188:191], v173 offset:1024
	ds_read_b128 v[192:195], v173 offset:2048
	ds_read_b128 v[200:203], v173 offset:3072
	ds_read_b128 v[204:207], v173 offset:4096
	ds_read_b128 v[208:211], v173 offset:5120
	ds_read_b128 v[212:215], v173 offset:6144
	ds_read_b128 v[216:219], v173 offset:7168
	global_load_lds_dwordx4 v[196:197], off
	v_lshl_add_u64 v[196:197], s[54:55], 0, v[138:139]
	s_add_i32 m0, s17, 0xe000
	s_nop 0
	global_load_lds_dwordx4 v[196:197], off
	s_waitcnt vmcnt(8)
	s_waitcnt lgkmcnt(0)
	s_barrier
	s_waitcnt lgkmcnt(0)
	v_mfma_f32_16x16x32_bf16 v[124:127], v[144:147], v[184:187], v[124:127]
	v_mfma_f32_16x16x32_bf16 v[120:123], v[152:155], v[184:187], v[120:123]
	v_mfma_f32_16x16x32_bf16 v[108:111], v[144:147], v[192:195], v[108:111]
	v_mfma_f32_16x16x32_bf16 v[104:107], v[152:155], v[192:195], v[104:107]
	v_mfma_f32_16x16x32_bf16 v[92:95], v[144:147], v[204:207], v[92:95]
	v_mfma_f32_16x16x32_bf16 v[88:91], v[152:155], v[204:207], v[88:91]
	v_mfma_f32_16x16x32_bf16 v[76:79], v[144:147], v[212:215], v[76:79]
	v_mfma_f32_16x16x32_bf16 v[72:75], v[152:155], v[212:215], v[72:75]
	v_mfma_f32_16x16x32_bf16 v[124:127], v[148:151], v[188:191], v[124:127]
	v_mfma_f32_16x16x32_bf16 v[120:123], v[156:159], v[188:191], v[120:123]
	v_mfma_f32_16x16x32_bf16 v[108:111], v[148:151], v[200:203], v[108:111]
	v_mfma_f32_16x16x32_bf16 v[104:107], v[156:159], v[200:203], v[104:107]
	v_mfma_f32_16x16x32_bf16 v[92:95], v[148:151], v[208:211], v[92:95]
	v_mfma_f32_16x16x32_bf16 v[88:91], v[156:159], v[208:211], v[88:91]
	v_mfma_f32_16x16x32_bf16 v[76:79], v[148:151], v[216:219], v[76:79]
	v_mfma_f32_16x16x32_bf16 v[72:75], v[156:159], v[216:219], v[72:75]
	v_mfma_f32_16x16x32_bf16 v[116:119], v[160:163], v[184:187], v[116:119]
	v_mfma_f32_16x16x32_bf16 v[112:115], v[176:179], v[184:187], v[112:115]
	v_mfma_f32_16x16x32_bf16 v[100:103], v[160:163], v[192:195], v[100:103]
	v_mfma_f32_16x16x32_bf16 v[96:99], v[176:179], v[192:195], v[96:99]
	v_mfma_f32_16x16x32_bf16 v[84:87], v[160:163], v[204:207], v[84:87]
	v_mfma_f32_16x16x32_bf16 v[80:83], v[176:179], v[204:207], v[80:83]
	v_mfma_f32_16x16x32_bf16 v[68:71], v[160:163], v[212:215], v[68:71]
	v_mfma_f32_16x16x32_bf16 v[64:67], v[176:179], v[212:215], v[64:67]
	v_mfma_f32_16x16x32_bf16 v[116:119], v[164:167], v[188:191], v[116:119]
	v_mfma_f32_16x16x32_bf16 v[112:115], v[180:183], v[188:191], v[112:115]
	v_mfma_f32_16x16x32_bf16 v[100:103], v[164:167], v[200:203], v[100:103]
	v_mfma_f32_16x16x32_bf16 v[96:99], v[180:183], v[200:203], v[96:99]
	v_mfma_f32_16x16x32_bf16 v[84:87], v[164:167], v[208:211], v[84:87]
	v_mfma_f32_16x16x32_bf16 v[80:83], v[180:183], v[208:211], v[80:83]
	v_mfma_f32_16x16x32_bf16 v[68:71], v[164:167], v[216:219], v[68:71]
	v_mfma_f32_16x16x32_bf16 v[64:67], v[180:183], v[216:219], v[64:67]
	s_barrier
	s_add_i32 s85, s78, s16
	v_lshl_add_u64 v[196:197], s[56:57], 0, v[130:131]
	s_mov_b32 m0, s85
	ds_read_b128 v[184:187], v173 offset:16384
	ds_read_b128 v[188:191], v173 offset:17408
	ds_read_b128 v[192:195], v173 offset:18432
	ds_read_b128 v[200:203], v173 offset:19456
	ds_read_b128 v[204:207], v173 offset:20480
	ds_read_b128 v[208:211], v173 offset:21504
	ds_read_b128 v[212:215], v173 offset:22528
	ds_read_b128 v[216:219], v173 offset:23552
	global_load_lds_dwordx4 v[196:197], off
	s_add_i32 m0, s85, 0x2000
	s_add_u32 s86, s56, 0xb0000
	v_lshl_add_u64 v[220:221], s[56:57], 0, v[134:135]
	s_addc_u32 s87, s57, 0
	s_add_i32 s85, s79, s16
	global_load_lds_dwordx4 v[220:221], off
	v_lshl_add_u64 v[224:225], s[86:87], 0, v[130:131]
	s_mov_b32 m0, s85
	v_lshl_add_u64 v[226:227], s[58:59], 0, v[132:133]
	global_load_lds_dwordx4 v[224:225], off
	v_lshl_add_u64 v[224:225], s[86:87], 0, v[134:135]
	s_add_i32 m0, s85, 0x2000
	s_nop 0
	global_load_lds_dwordx4 v[224:225], off
	v_lshl_add_u64 v[224:225], s[58:59], 0, v[128:129]
	s_mov_b32 m0, s17
	s_nop 0
	global_load_lds_dwordx4 v[224:225], off
	s_mov_b32 m0, s39
	s_nop 0
	global_load_lds_dwordx4 v[226:227], off
	s_waitcnt vmcnt(8)
	s_waitcnt lgkmcnt(0)
	s_barrier
	s_waitcnt lgkmcnt(0)
	v_mfma_f32_16x16x32_bf16 v[60:63], v[144:147], v[184:187], v[60:63]
	v_mfma_f32_16x16x32_bf16 v[56:59], v[152:155], v[184:187], v[56:59]
	v_mfma_f32_16x16x32_bf16 v[44:47], v[144:147], v[192:195], v[44:47]
	v_mfma_f32_16x16x32_bf16 v[40:43], v[152:155], v[192:195], v[40:43]
	v_mfma_f32_16x16x32_bf16 v[28:31], v[144:147], v[204:207], v[28:31]
	v_mfma_f32_16x16x32_bf16 v[24:27], v[152:155], v[204:207], v[24:27]
	v_mfma_f32_16x16x32_bf16 v[12:15], v[144:147], v[212:215], v[12:15]
	v_mfma_f32_16x16x32_bf16 v[8:11], v[152:155], v[212:215], v[8:11]
	v_mfma_f32_16x16x32_bf16 v[60:63], v[148:151], v[188:191], v[60:63]
	v_mfma_f32_16x16x32_bf16 v[56:59], v[156:159], v[188:191], v[56:59]
	v_mfma_f32_16x16x32_bf16 v[44:47], v[148:151], v[200:203], v[44:47]
	v_mfma_f32_16x16x32_bf16 v[40:43], v[156:159], v[200:203], v[40:43]
	v_mfma_f32_16x16x32_bf16 v[28:31], v[148:151], v[208:211], v[28:31]
	v_mfma_f32_16x16x32_bf16 v[24:27], v[156:159], v[208:211], v[24:27]
	v_mfma_f32_16x16x32_bf16 v[12:15], v[148:151], v[216:219], v[12:15]
	v_mfma_f32_16x16x32_bf16 v[8:11], v[156:159], v[216:219], v[8:11]
	v_mfma_f32_16x16x32_bf16 v[52:55], v[160:163], v[184:187], v[52:55]
	v_mfma_f32_16x16x32_bf16 v[48:51], v[176:179], v[184:187], v[48:51]
	v_mfma_f32_16x16x32_bf16 v[36:39], v[160:163], v[192:195], v[36:39]
	v_mfma_f32_16x16x32_bf16 v[32:35], v[176:179], v[192:195], v[32:35]
	v_mfma_f32_16x16x32_bf16 v[20:23], v[160:163], v[204:207], v[20:23]
	v_mfma_f32_16x16x32_bf16 v[16:19], v[176:179], v[204:207], v[16:19]
	v_mfma_f32_16x16x32_bf16 v[4:7], v[160:163], v[212:215], v[4:7]
	v_mfma_f32_16x16x32_bf16 v[0:3], v[176:179], v[212:215], v[0:3]
	v_mfma_f32_16x16x32_bf16 v[52:55], v[164:167], v[188:191], v[52:55]
	v_mfma_f32_16x16x32_bf16 v[48:51], v[180:183], v[188:191], v[48:51]
	v_mfma_f32_16x16x32_bf16 v[36:39], v[164:167], v[200:203], v[36:39]
	v_mfma_f32_16x16x32_bf16 v[32:35], v[180:183], v[200:203], v[32:35]
	v_mfma_f32_16x16x32_bf16 v[20:23], v[164:167], v[208:211], v[20:23]
	v_mfma_f32_16x16x32_bf16 v[16:19], v[180:183], v[208:211], v[16:19]
	v_mfma_f32_16x16x32_bf16 v[4:7], v[164:167], v[216:219], v[4:7]
	v_mfma_f32_16x16x32_bf16 v[0:3], v[180:183], v[216:219], v[0:3]
	s_barrier
	s_add_i32 s85, 0, 0x18000
	s_add_i32 s86, 0, 0x1c000
	v_add_u32_e32 v156, s85, v169
	v_add_u32_e32 v175, s86, v169
	ds_read_b128 v[144:147], v156
	ds_read_b128 v[148:151], v156 offset:1024
	ds_read_b128 v[152:155], v156 offset:2048
	ds_read_b128 v[156:159], v156 offset:3072
	ds_read_b128 v[160:163], v175
	ds_read_b128 v[164:167], v175 offset:1024
	ds_read_b128 v[176:179], v175 offset:2048
	ds_read_b128 v[180:183], v175 offset:3072
	s_add_u32 s58, s58, 0xb0000
	s_addc_u32 s59, s59, 0
	s_mov_b32 m0, s45
	v_lshl_add_u64 v[228:229], s[58:59], 0, v[128:129]
	ds_read_b128 v[184:187], v173 offset:32768
	ds_read_b128 v[188:191], v173 offset:33792
	ds_read_b128 v[192:195], v173 offset:34816
	ds_read_b128 v[200:203], v173 offset:35840
	ds_read_b128 v[204:207], v173 offset:36864
	ds_read_b128 v[208:211], v173 offset:37888
	ds_read_b128 v[212:215], v173 offset:38912
	ds_read_b128 v[216:219], v173 offset:39936
	global_load_lds_dwordx4 v[228:229], off
	v_lshl_add_u64 v[228:229], s[58:59], 0, v[132:133]
	s_mov_b32 m0, s60
	s_nop 0
	global_load_lds_dwordx4 v[228:229], off
	s_waitcnt vmcnt(8)
	s_waitcnt lgkmcnt(0)
	s_barrier
	s_waitcnt lgkmcnt(0)
	v_mfma_f32_16x16x32_bf16 v[124:127], v[144:147], v[184:187], v[124:127]
	v_mfma_f32_16x16x32_bf16 v[120:123], v[152:155], v[184:187], v[120:123]
	v_mfma_f32_16x16x32_bf16 v[108:111], v[144:147], v[192:195], v[108:111]
	v_mfma_f32_16x16x32_bf16 v[104:107], v[152:155], v[192:195], v[104:107]
	v_mfma_f32_16x16x32_bf16 v[92:95], v[144:147], v[204:207], v[92:95]
	v_mfma_f32_16x16x32_bf16 v[88:91], v[152:155], v[204:207], v[88:91]
	v_mfma_f32_16x16x32_bf16 v[76:79], v[144:147], v[212:215], v[76:79]
	v_mfma_f32_16x16x32_bf16 v[72:75], v[152:155], v[212:215], v[72:75]
	v_mfma_f32_16x16x32_bf16 v[124:127], v[148:151], v[188:191], v[124:127]
	v_mfma_f32_16x16x32_bf16 v[120:123], v[156:159], v[188:191], v[120:123]
	v_mfma_f32_16x16x32_bf16 v[108:111], v[148:151], v[200:203], v[108:111]
	v_mfma_f32_16x16x32_bf16 v[104:107], v[156:159], v[200:203], v[104:107]
	v_mfma_f32_16x16x32_bf16 v[92:95], v[148:151], v[208:211], v[92:95]
	v_mfma_f32_16x16x32_bf16 v[88:91], v[156:159], v[208:211], v[88:91]
	v_mfma_f32_16x16x32_bf16 v[76:79], v[148:151], v[216:219], v[76:79]
	v_mfma_f32_16x16x32_bf16 v[72:75], v[156:159], v[216:219], v[72:75]
	v_mfma_f32_16x16x32_bf16 v[116:119], v[160:163], v[184:187], v[116:119]
	v_mfma_f32_16x16x32_bf16 v[112:115], v[176:179], v[184:187], v[112:115]
	v_mfma_f32_16x16x32_bf16 v[100:103], v[160:163], v[192:195], v[100:103]
	v_mfma_f32_16x16x32_bf16 v[96:99], v[176:179], v[192:195], v[96:99]
	v_mfma_f32_16x16x32_bf16 v[84:87], v[160:163], v[204:207], v[84:87]
	v_mfma_f32_16x16x32_bf16 v[80:83], v[176:179], v[204:207], v[80:83]
	v_mfma_f32_16x16x32_bf16 v[68:71], v[160:163], v[212:215], v[68:71]
	v_mfma_f32_16x16x32_bf16 v[64:67], v[176:179], v[212:215], v[64:67]
	v_mfma_f32_16x16x32_bf16 v[116:119], v[164:167], v[188:191], v[116:119]
	v_mfma_f32_16x16x32_bf16 v[112:115], v[180:183], v[188:191], v[112:115]
	v_mfma_f32_16x16x32_bf16 v[100:103], v[164:167], v[200:203], v[100:103]
	v_mfma_f32_16x16x32_bf16 v[96:99], v[180:183], v[200:203], v[96:99]
	v_mfma_f32_16x16x32_bf16 v[84:87], v[164:167], v[208:211], v[84:87]
	v_mfma_f32_16x16x32_bf16 v[80:83], v[180:183], v[208:211], v[80:83]
	v_mfma_f32_16x16x32_bf16 v[68:71], v[164:167], v[216:219], v[68:71]
	v_mfma_f32_16x16x32_bf16 v[64:67], v[180:183], v[216:219], v[64:67]
	s_barrier
	s_add_i32 s58, s85, s16
	v_lshl_add_u64 v[196:197], v[196:197], 0, s[18:19]
	s_mov_b32 m0, s58
	ds_read_b128 v[184:187], v173 offset:49152
	ds_read_b128 v[188:191], v173 offset:50176
	ds_read_b128 v[192:195], v173 offset:51200
	ds_read_b128 v[200:203], v173 offset:52224
	ds_read_b128 v[204:207], v173 offset:53248
	ds_read_b128 v[208:211], v173 offset:54272
	ds_read_b128 v[212:215], v173 offset:55296
	ds_read_b128 v[216:219], v173 offset:56320
	global_load_lds_dwordx4 v[196:197], off
	s_add_i32 m0, s58, 0x2000
	s_add_u32 s56, s56, 0xb0080
	v_lshl_add_u64 v[196:197], v[220:221], 0, s[18:19]
	s_addc_u32 s57, s57, 0
	s_add_i32 s58, s86, s16
	global_load_lds_dwordx4 v[196:197], off
	v_lshl_add_u64 v[196:197], s[56:57], 0, v[130:131]
	s_mov_b32 m0, s58
	s_nop 0
	global_load_lds_dwordx4 v[196:197], off
	v_lshl_add_u64 v[196:197], s[56:57], 0, v[134:135]
	s_add_i32 m0, s58, 0x2000
	s_nop 0
	global_load_lds_dwordx4 v[196:197], off
	v_lshl_add_u64 v[196:197], v[224:225], 0, s[18:19]
	s_mov_b32 m0, s67
	s_nop 0
	global_load_lds_dwordx4 v[196:197], off
	v_lshl_add_u64 v[196:197], v[226:227], 0, s[18:19]
	s_mov_b32 m0, s70
	s_nop 0
	global_load_lds_dwordx4 v[196:197], off
	s_waitcnt vmcnt(8)
	s_waitcnt lgkmcnt(0)
	s_barrier
	s_waitcnt lgkmcnt(0)
	v_mfma_f32_16x16x32_bf16 v[60:63], v[144:147], v[184:187], v[60:63]
	v_mfma_f32_16x16x32_bf16 v[56:59], v[152:155], v[184:187], v[56:59]
	v_mfma_f32_16x16x32_bf16 v[44:47], v[144:147], v[192:195], v[44:47]
	v_mfma_f32_16x16x32_bf16 v[40:43], v[152:155], v[192:195], v[40:43]
	v_mfma_f32_16x16x32_bf16 v[28:31], v[144:147], v[204:207], v[28:31]
	v_mfma_f32_16x16x32_bf16 v[24:27], v[152:155], v[204:207], v[24:27]
	v_mfma_f32_16x16x32_bf16 v[12:15], v[144:147], v[212:215], v[12:15]
	v_mfma_f32_16x16x32_bf16 v[8:11], v[152:155], v[212:215], v[8:11]
	v_mfma_f32_16x16x32_bf16 v[60:63], v[148:151], v[188:191], v[60:63]
	v_mfma_f32_16x16x32_bf16 v[56:59], v[156:159], v[188:191], v[56:59]
	v_mfma_f32_16x16x32_bf16 v[44:47], v[148:151], v[200:203], v[44:47]
	v_mfma_f32_16x16x32_bf16 v[40:43], v[156:159], v[200:203], v[40:43]
	v_mfma_f32_16x16x32_bf16 v[28:31], v[148:151], v[208:211], v[28:31]
	v_mfma_f32_16x16x32_bf16 v[24:27], v[156:159], v[208:211], v[24:27]
	v_mfma_f32_16x16x32_bf16 v[12:15], v[148:151], v[216:219], v[12:15]
	v_mfma_f32_16x16x32_bf16 v[8:11], v[156:159], v[216:219], v[8:11]
	v_mfma_f32_16x16x32_bf16 v[52:55], v[160:163], v[184:187], v[52:55]
	v_mfma_f32_16x16x32_bf16 v[48:51], v[176:179], v[184:187], v[48:51]
	v_mfma_f32_16x16x32_bf16 v[36:39], v[160:163], v[192:195], v[36:39]
	v_mfma_f32_16x16x32_bf16 v[32:35], v[176:179], v[192:195], v[32:35]
	v_mfma_f32_16x16x32_bf16 v[20:23], v[160:163], v[204:207], v[20:23]
	v_mfma_f32_16x16x32_bf16 v[16:19], v[176:179], v[204:207], v[16:19]
	v_mfma_f32_16x16x32_bf16 v[4:7], v[160:163], v[212:215], v[4:7]
	v_mfma_f32_16x16x32_bf16 v[0:3], v[176:179], v[212:215], v[0:3]
	v_mfma_f32_16x16x32_bf16 v[52:55], v[164:167], v[188:191], v[52:55]
	v_mfma_f32_16x16x32_bf16 v[48:51], v[180:183], v[188:191], v[48:51]
	v_mfma_f32_16x16x32_bf16 v[36:39], v[164:167], v[200:203], v[36:39]
	v_mfma_f32_16x16x32_bf16 v[32:35], v[180:183], v[200:203], v[32:35]
	v_mfma_f32_16x16x32_bf16 v[20:23], v[164:167], v[208:211], v[20:23]
	v_mfma_f32_16x16x32_bf16 v[16:19], v[180:183], v[208:211], v[16:19]
	v_mfma_f32_16x16x32_bf16 v[4:7], v[164:167], v[216:219], v[4:7]
	v_mfma_f32_16x16x32_bf16 v[0:3], v[180:183], v[216:219], v[0:3]
	s_barrier
	s_add_i32 s84, s84, 2
	s_add_u32 s54, s54, 0x100
	s_addc_u32 s55, s55, 0
	s_add_u32 s82, s82, 0x100
	s_addc_u32 s83, s83, 0
	s_cmp_gt_u32 s84, 41
	s_cbranch_scc0 .LBB0_340
	s_and_b64 vcc, exec, s[20:21]
	s_cbranch_vccz .LBB0_343
	s_barrier

.LBB0_476:
	v_add_u32_e32 v164, s71, v188
	ds_read_b128 v[128:131], v210
	ds_read_b128 v[132:135], v210 offset:1024
	ds_read_b128 v[136:139], v210 offset:2048
	ds_read_b128 v[140:143], v210 offset:3072
	ds_read_b128 v[144:147], v164
	ds_read_b128 v[148:151], v164 offset:1024
	ds_read_b128 v[152:155], v164 offset:2048
	ds_read_b128 v[178:181], v164 offset:3072
	s_add_u32 s6, s4, 0xfffc0080
	s_addc_u32 s7, s5, -1
	s_cmp_eq_u32 s91, 12
	s_cselect_b32 s13, s10, s7
	s_cselect_b32 s12, s11, s6
	s_cselect_b32 s7, s20, s90
	s_cselect_b32 s6, s83, s85
	v_lshl_add_u64 v[186:187], s[4:5], 0, v[174:175]
	s_add_i32 m0, s25, 0xc000
	ds_read_b128 v[182:185], v206
	ds_read_b128 v[218:221], v206 offset:1024
	ds_read_b128 v[224:227], v206 offset:2048
	ds_read_b128 v[228:231], v206 offset:3072
	ds_read_b128 v[232:235], v206 offset:4096
	ds_read_b128 v[236:239], v206 offset:5120
	ds_read_b128 v[240:243], v206 offset:6144
	ds_read_b128 v[244:247], v206 offset:7168
	global_load_lds_dwordx4 v[186:187], off
	v_lshl_add_u64 v[186:187], s[4:5], 0, v[176:177]
	s_add_i32 m0, s25, 0xe000
	s_nop 0
	global_load_lds_dwordx4 v[186:187], off
	s_waitcnt vmcnt(8)
	s_waitcnt lgkmcnt(0)
	s_barrier
	s_waitcnt lgkmcnt(0)
	v_mfma_f32_16x16x32_bf16 v[112:115], v[128:131], v[182:185], v[112:115]
	v_mfma_f32_16x16x32_bf16 v[116:119], v[136:139], v[182:185], v[116:119]
	v_mfma_f32_16x16x32_bf16 v[80:83], v[128:131], v[224:227], v[80:83]
	v_mfma_f32_16x16x32_bf16 v[88:91], v[136:139], v[224:227], v[88:91]
	v_mfma_f32_16x16x32_bf16 v[64:67], v[128:131], v[232:235], v[64:67]
	v_mfma_f32_16x16x32_bf16 v[68:71], v[136:139], v[232:235], v[68:71]
	v_mfma_f32_16x16x32_bf16 v[48:51], v[128:131], v[240:243], v[48:51]
	v_mfma_f32_16x16x32_bf16 v[52:55], v[136:139], v[240:243], v[52:55]
	v_mfma_f32_16x16x32_bf16 v[112:115], v[132:135], v[218:221], v[112:115]
	v_mfma_f32_16x16x32_bf16 v[116:119], v[140:143], v[218:221], v[116:119]
	v_mfma_f32_16x16x32_bf16 v[80:83], v[132:135], v[228:231], v[80:83]
	v_mfma_f32_16x16x32_bf16 v[88:91], v[140:143], v[228:231], v[88:91]
	v_mfma_f32_16x16x32_bf16 v[64:67], v[132:135], v[236:239], v[64:67]
	v_mfma_f32_16x16x32_bf16 v[68:71], v[140:143], v[236:239], v[68:71]
	v_mfma_f32_16x16x32_bf16 v[48:51], v[132:135], v[244:247], v[48:51]
	v_mfma_f32_16x16x32_bf16 v[52:55], v[140:143], v[244:247], v[52:55]
	v_mfma_f32_16x16x32_bf16 v[120:123], v[144:147], v[182:185], v[120:123]
	v_mfma_f32_16x16x32_bf16 v[124:127], v[152:155], v[182:185], v[124:127]
	v_mfma_f32_16x16x32_bf16 v[96:99], v[144:147], v[224:227], v[96:99]
	v_mfma_f32_16x16x32_bf16 v[104:107], v[152:155], v[224:227], v[104:107]
	v_mfma_f32_16x16x32_bf16 v[72:75], v[144:147], v[232:235], v[72:75]
	v_mfma_f32_16x16x32_bf16 v[76:79], v[152:155], v[232:235], v[76:79]
	v_mfma_f32_16x16x32_bf16 v[56:59], v[144:147], v[240:243], v[56:59]
	v_mfma_f32_16x16x32_bf16 v[60:63], v[152:155], v[240:243], v[60:63]
	v_mfma_f32_16x16x32_bf16 v[120:123], v[148:151], v[218:221], v[120:123]
	v_mfma_f32_16x16x32_bf16 v[124:127], v[178:181], v[218:221], v[124:127]
	v_mfma_f32_16x16x32_bf16 v[96:99], v[148:151], v[228:231], v[96:99]
	v_mfma_f32_16x16x32_bf16 v[104:107], v[178:181], v[228:231], v[104:107]
	v_mfma_f32_16x16x32_bf16 v[72:75], v[148:151], v[236:239], v[72:75]
	v_mfma_f32_16x16x32_bf16 v[76:79], v[178:181], v[236:239], v[76:79]
	v_mfma_f32_16x16x32_bf16 v[56:59], v[148:151], v[244:247], v[56:59]
	v_mfma_f32_16x16x32_bf16 v[60:63], v[178:181], v[244:247], v[60:63]
	s_barrier
	s_add_i32 s92, s70, s62
	v_lshl_add_u64 v[186:187], s[6:7], 0, v[158:159]
	s_mov_b32 m0, s92
	ds_read_b128 v[182:185], v206 offset:16384
	ds_read_b128 v[218:221], v206 offset:17408
	ds_read_b128 v[224:227], v206 offset:18432
	ds_read_b128 v[228:231], v206 offset:19456
	ds_read_b128 v[232:235], v206 offset:20480
	ds_read_b128 v[236:239], v206 offset:21504
	ds_read_b128 v[240:243], v206 offset:22528
	ds_read_b128 v[244:247], v206 offset:23552
	global_load_lds_dwordx4 v[186:187], off
	s_add_i32 m0, s92, 0x2000
	s_add_u32 s92, s6, 0x40000
	v_lshl_add_u64 v[248:249], s[6:7], 0, v[162:163]
	s_addc_u32 s93, s7, 0
	s_add_i32 s94, s71, s62
	global_load_lds_dwordx4 v[248:249], off
	v_lshl_add_u64 v[250:251], s[92:93], 0, v[158:159]
	s_mov_b32 m0, s94
	v_lshl_add_u64 v[252:253], s[12:13], 0, v[160:161]
	global_load_lds_dwordx4 v[250:251], off
	v_lshl_add_u64 v[250:251], s[92:93], 0, v[162:163]
	s_add_i32 m0, s94, 0x2000
	s_nop 0
	global_load_lds_dwordx4 v[250:251], off
	v_lshl_add_u64 v[250:251], s[12:13], 0, v[156:157]
	s_mov_b32 m0, s25
	s_nop 0
	global_load_lds_dwordx4 v[250:251], off
	s_mov_b32 m0, s63
	s_nop 0
	global_load_lds_dwordx4 v[252:253], off
	s_waitcnt vmcnt(8)
	s_waitcnt lgkmcnt(0)
	s_barrier
	s_waitcnt lgkmcnt(0)
	v_mfma_f32_16x16x32_bf16 v[32:35], v[128:131], v[182:185], v[32:35]
	v_mfma_f32_16x16x32_bf16 v[36:39], v[136:139], v[182:185], v[36:39]
	v_mfma_f32_16x16x32_bf16 v[16:19], v[128:131], v[224:227], v[16:19]
	v_mfma_f32_16x16x32_bf16 v[20:23], v[136:139], v[224:227], v[20:23]
	v_mfma_f32_16x16x32_bf16 v[0:3], v[128:131], v[232:235], v[0:3]
	v_mfma_f32_16x16x32_bf16 v[4:7], v[136:139], v[232:235], v[4:7]
	v_mfma_f32_16x16x32_bf16 v[84:87], v[128:131], v[240:243], v[84:87]
	v_mfma_f32_16x16x32_bf16 v[92:95], v[136:139], v[240:243], v[92:95]
	v_mfma_f32_16x16x32_bf16 v[32:35], v[132:135], v[218:221], v[32:35]
	v_mfma_f32_16x16x32_bf16 v[36:39], v[140:143], v[218:221], v[36:39]
	v_mfma_f32_16x16x32_bf16 v[16:19], v[132:135], v[228:231], v[16:19]
	v_mfma_f32_16x16x32_bf16 v[20:23], v[140:143], v[228:231], v[20:23]
	v_mfma_f32_16x16x32_bf16 v[0:3], v[132:135], v[236:239], v[0:3]
	v_mfma_f32_16x16x32_bf16 v[4:7], v[140:143], v[236:239], v[4:7]
	v_mfma_f32_16x16x32_bf16 v[84:87], v[132:135], v[244:247], v[84:87]
	v_mfma_f32_16x16x32_bf16 v[92:95], v[140:143], v[244:247], v[92:95]
	v_mfma_f32_16x16x32_bf16 v[40:43], v[144:147], v[182:185], v[40:43]
	v_mfma_f32_16x16x32_bf16 v[44:47], v[152:155], v[182:185], v[44:47]
	v_mfma_f32_16x16x32_bf16 v[24:27], v[144:147], v[224:227], v[24:27]
	v_mfma_f32_16x16x32_bf16 v[28:31], v[152:155], v[224:227], v[28:31]
	v_mfma_f32_16x16x32_bf16 v[8:11], v[144:147], v[232:235], v[8:11]
	v_mfma_f32_16x16x32_bf16 v[12:15], v[152:155], v[232:235], v[12:15]
	v_mfma_f32_16x16x32_bf16 v[100:103], v[144:147], v[240:243], v[100:103]
	v_mfma_f32_16x16x32_bf16 v[108:111], v[152:155], v[240:243], v[108:111]
	v_mfma_f32_16x16x32_bf16 v[40:43], v[148:151], v[218:221], v[40:43]
	v_mfma_f32_16x16x32_bf16 v[44:47], v[178:181], v[218:221], v[44:47]
	v_mfma_f32_16x16x32_bf16 v[24:27], v[148:151], v[228:231], v[24:27]
	v_mfma_f32_16x16x32_bf16 v[28:31], v[178:181], v[228:231], v[28:31]
	v_mfma_f32_16x16x32_bf16 v[8:11], v[148:151], v[236:239], v[8:11]
	v_mfma_f32_16x16x32_bf16 v[12:15], v[178:181], v[236:239], v[12:15]
	v_mfma_f32_16x16x32_bf16 v[100:103], v[148:151], v[244:247], v[100:103]
	v_mfma_f32_16x16x32_bf16 v[108:111], v[178:181], v[244:247], v[108:111]
	s_barrier
	s_add_i32 s92, 0, 0x18000
	s_add_i32 s93, 0, 0x1c000
	v_add_u32_e32 v140, s92, v188
	v_add_u32_e32 v164, s93, v188
	ds_read_b128 v[128:131], v140
	ds_read_b128 v[132:135], v140 offset:1024
	ds_read_b128 v[136:139], v140 offset:2048
	ds_read_b128 v[140:143], v140 offset:3072
	ds_read_b128 v[144:147], v164
	ds_read_b128 v[148:151], v164 offset:1024
	ds_read_b128 v[152:155], v164 offset:2048
	ds_read_b128 v[178:181], v164 offset:3072
	s_add_u32 s12, s12, 0x40000
	s_addc_u32 s13, s13, 0
	s_mov_b32 m0, s64
	v_lshl_add_u64 v[200:201], s[12:13], 0, v[156:157]
	ds_read_b128 v[182:185], v206 offset:32768
	ds_read_b128 v[218:221], v206 offset:33792
	ds_read_b128 v[224:227], v206 offset:34816
	ds_read_b128 v[228:231], v206 offset:35840
	ds_read_b128 v[232:235], v206 offset:36864
	ds_read_b128 v[236:239], v206 offset:37888
	ds_read_b128 v[240:243], v206 offset:38912
	ds_read_b128 v[244:247], v206 offset:39936
	global_load_lds_dwordx4 v[200:201], off
	v_lshl_add_u64 v[200:201], s[12:13], 0, v[160:161]
	s_mov_b32 m0, s65
	s_nop 0
	global_load_lds_dwordx4 v[200:201], off
	s_waitcnt vmcnt(8)
	s_waitcnt lgkmcnt(0)
	s_barrier
	s_waitcnt lgkmcnt(0)
	v_mfma_f32_16x16x32_bf16 v[112:115], v[128:131], v[182:185], v[112:115]
	v_mfma_f32_16x16x32_bf16 v[116:119], v[136:139], v[182:185], v[116:119]
	v_mfma_f32_16x16x32_bf16 v[80:83], v[128:131], v[224:227], v[80:83]
	v_mfma_f32_16x16x32_bf16 v[88:91], v[136:139], v[224:227], v[88:91]
	v_mfma_f32_16x16x32_bf16 v[64:67], v[128:131], v[232:235], v[64:67]
	v_mfma_f32_16x16x32_bf16 v[68:71], v[136:139], v[232:235], v[68:71]
	v_mfma_f32_16x16x32_bf16 v[48:51], v[128:131], v[240:243], v[48:51]
	v_mfma_f32_16x16x32_bf16 v[52:55], v[136:139], v[240:243], v[52:55]
	v_mfma_f32_16x16x32_bf16 v[112:115], v[132:135], v[218:221], v[112:115]
	v_mfma_f32_16x16x32_bf16 v[116:119], v[140:143], v[218:221], v[116:119]
	v_mfma_f32_16x16x32_bf16 v[80:83], v[132:135], v[228:231], v[80:83]
	v_mfma_f32_16x16x32_bf16 v[88:91], v[140:143], v[228:231], v[88:91]
	v_mfma_f32_16x16x32_bf16 v[64:67], v[132:135], v[236:239], v[64:67]
	v_mfma_f32_16x16x32_bf16 v[68:71], v[140:143], v[236:239], v[68:71]
	v_mfma_f32_16x16x32_bf16 v[48:51], v[132:135], v[244:247], v[48:51]
	v_mfma_f32_16x16x32_bf16 v[52:55], v[140:143], v[244:247], v[52:55]
	v_mfma_f32_16x16x32_bf16 v[120:123], v[144:147], v[182:185], v[120:123]
	v_mfma_f32_16x16x32_bf16 v[124:127], v[152:155], v[182:185], v[124:127]
	v_mfma_f32_16x16x32_bf16 v[96:99], v[144:147], v[224:227], v[96:99]
	v_mfma_f32_16x16x32_bf16 v[104:107], v[152:155], v[224:227], v[104:107]
	v_mfma_f32_16x16x32_bf16 v[72:75], v[144:147], v[232:235], v[72:75]
	v_mfma_f32_16x16x32_bf16 v[76:79], v[152:155], v[232:235], v[76:79]
	v_mfma_f32_16x16x32_bf16 v[56:59], v[144:147], v[240:243], v[56:59]
	v_mfma_f32_16x16x32_bf16 v[60:63], v[152:155], v[240:243], v[60:63]
	v_mfma_f32_16x16x32_bf16 v[120:123], v[148:151], v[218:221], v[120:123]
	v_mfma_f32_16x16x32_bf16 v[124:127], v[178:181], v[218:221], v[124:127]
	v_mfma_f32_16x16x32_bf16 v[96:99], v[148:151], v[228:231], v[96:99]
	v_mfma_f32_16x16x32_bf16 v[104:107], v[178:181], v[228:231], v[104:107]
	v_mfma_f32_16x16x32_bf16 v[72:75], v[148:151], v[236:239], v[72:75]
	v_mfma_f32_16x16x32_bf16 v[76:79], v[178:181], v[236:239], v[76:79]
	v_mfma_f32_16x16x32_bf16 v[56:59], v[148:151], v[244:247], v[56:59]
	v_mfma_f32_16x16x32_bf16 v[60:63], v[178:181], v[244:247], v[60:63]
	s_barrier
	s_add_i32 s12, s92, s62
	v_lshl_add_u64 v[186:187], v[186:187], 0, s[50:51]
	s_mov_b32 m0, s12
	ds_read_b128 v[182:185], v206 offset:49152
	ds_read_b128 v[218:221], v206 offset:50176
	ds_read_b128 v[224:227], v206 offset:51200
	ds_read_b128 v[228:231], v206 offset:52224
	ds_read_b128 v[232:235], v206 offset:53248
	ds_read_b128 v[236:239], v206 offset:54272
	ds_read_b128 v[240:243], v206 offset:55296
	ds_read_b128 v[244:247], v206 offset:56320
	global_load_lds_dwordx4 v[186:187], off
	s_add_i32 m0, s12, 0x2000
	s_add_u32 s6, s6, 0x40080
	v_lshl_add_u64 v[186:187], v[248:249], 0, s[50:51]
	s_addc_u32 s7, s7, 0
	s_add_i32 s12, s93, s62
	global_load_lds_dwordx4 v[186:187], off
	v_lshl_add_u64 v[186:187], s[6:7], 0, v[158:159]
	s_mov_b32 m0, s12
	s_nop 0
	global_load_lds_dwordx4 v[186:187], off
	v_lshl_add_u64 v[186:187], s[6:7], 0, v[162:163]
	s_add_i32 m0, s12, 0x2000
	s_nop 0
	global_load_lds_dwordx4 v[186:187], off
	v_lshl_add_u64 v[186:187], v[250:251], 0, s[50:51]
	s_mov_b32 m0, s78
	s_nop 0
	global_load_lds_dwordx4 v[186:187], off
	v_lshl_add_u64 v[186:187], v[252:253], 0, s[50:51]
	s_mov_b32 m0, s79
	s_nop 0
	global_load_lds_dwordx4 v[186:187], off
	s_waitcnt vmcnt(8)
	s_waitcnt lgkmcnt(0)
	s_barrier
	s_waitcnt lgkmcnt(0)
	v_mfma_f32_16x16x32_bf16 v[32:35], v[128:131], v[182:185], v[32:35]
	v_mfma_f32_16x16x32_bf16 v[36:39], v[136:139], v[182:185], v[36:39]
	v_mfma_f32_16x16x32_bf16 v[16:19], v[128:131], v[224:227], v[16:19]
	v_mfma_f32_16x16x32_bf16 v[20:23], v[136:139], v[224:227], v[20:23]
	v_mfma_f32_16x16x32_bf16 v[0:3], v[128:131], v[232:235], v[0:3]
	v_mfma_f32_16x16x32_bf16 v[4:7], v[136:139], v[232:235], v[4:7]
	v_mfma_f32_16x16x32_bf16 v[84:87], v[128:131], v[240:243], v[84:87]
	v_mfma_f32_16x16x32_bf16 v[92:95], v[136:139], v[240:243], v[92:95]
	v_mfma_f32_16x16x32_bf16 v[32:35], v[132:135], v[218:221], v[32:35]
	v_mfma_f32_16x16x32_bf16 v[36:39], v[140:143], v[218:221], v[36:39]
	v_mfma_f32_16x16x32_bf16 v[16:19], v[132:135], v[228:231], v[16:19]
	v_mfma_f32_16x16x32_bf16 v[20:23], v[140:143], v[228:231], v[20:23]
	v_mfma_f32_16x16x32_bf16 v[0:3], v[132:135], v[236:239], v[0:3]
	v_mfma_f32_16x16x32_bf16 v[4:7], v[140:143], v[236:239], v[4:7]
	v_mfma_f32_16x16x32_bf16 v[84:87], v[132:135], v[244:247], v[84:87]
	v_mfma_f32_16x16x32_bf16 v[92:95], v[140:143], v[244:247], v[92:95]
	v_mfma_f32_16x16x32_bf16 v[40:43], v[144:147], v[182:185], v[40:43]
	v_mfma_f32_16x16x32_bf16 v[44:47], v[152:155], v[182:185], v[44:47]
	v_mfma_f32_16x16x32_bf16 v[24:27], v[144:147], v[224:227], v[24:27]
	v_mfma_f32_16x16x32_bf16 v[28:31], v[152:155], v[224:227], v[28:31]
	v_mfma_f32_16x16x32_bf16 v[8:11], v[144:147], v[232:235], v[8:11]
	v_mfma_f32_16x16x32_bf16 v[12:15], v[152:155], v[232:235], v[12:15]
	v_mfma_f32_16x16x32_bf16 v[100:103], v[144:147], v[240:243], v[100:103]
	v_mfma_f32_16x16x32_bf16 v[108:111], v[152:155], v[240:243], v[108:111]
	v_mfma_f32_16x16x32_bf16 v[40:43], v[148:151], v[218:221], v[40:43]
	v_mfma_f32_16x16x32_bf16 v[44:47], v[178:181], v[218:221], v[44:47]
	v_mfma_f32_16x16x32_bf16 v[24:27], v[148:151], v[228:231], v[24:27]
	v_mfma_f32_16x16x32_bf16 v[28:31], v[178:181], v[228:231], v[28:31]
	v_mfma_f32_16x16x32_bf16 v[8:11], v[148:151], v[236:239], v[8:11]
	v_mfma_f32_16x16x32_bf16 v[12:15], v[178:181], v[236:239], v[12:15]
	v_mfma_f32_16x16x32_bf16 v[100:103], v[148:151], v[244:247], v[100:103]
	v_mfma_f32_16x16x32_bf16 v[108:111], v[178:181], v[244:247], v[108:111]
	s_barrier
	s_add_i32 s91, s91, 2
	s_add_u32 s4, s4, 0x100
	s_addc_u32 s5, s5, 0
	s_add_u32 s85, s85, 0x100
	s_addc_u32 s90, s90, 0
	s_cmp_gt_u32 s91, 13
	s_cbranch_scc0 .LBB0_476
	s_and_b64 vcc, exec, s[52:53]
	s_cbranch_vccz .LBB0_479
	s_barrier

.LBB0_1471:
	ds_read_b128 v[144:147], v159
	ds_read_b128 v[162:165], v159 offset:1024
	ds_read_b128 v[166:169], v159 offset:2048
	ds_read_b128 v[170:173], v159 offset:3072
	ds_read_b128 v[174:177], v160
	ds_read_b128 v[178:181], v160 offset:1024
	ds_read_b128 v[182:185], v160 offset:2048
	ds_read_b128 v[186:189], v160 offset:3072
	s_add_u32 s46, s44, 0xfffe0080
	s_addc_u32 s47, s45, -1
	s_cmp_eq_u32 s66, 4
	s_cselect_b32 s49, s10, s47
	s_cselect_b32 s48, s11, s46
	s_cselect_b32 s47, s19, s65
	s_cselect_b32 s46, s21, s64
	v_lshl_add_u64 v[224:225], s[44:45], 0, v[136:137]
	s_add_i32 m0, s43, 0xc000
	ds_read_b128 v[190:193], v161
	ds_read_b128 v[194:197], v161 offset:1024
	ds_read_b128 v[200:203], v161 offset:2048
	ds_read_b128 v[204:207], v161 offset:3072
	ds_read_b128 v[208:211], v161 offset:4096
	ds_read_b128 v[212:215], v161 offset:5120
	ds_read_b128 v[216:219], v161 offset:6144
	ds_read_b128 v[220:223], v161 offset:7168
	global_load_lds_dwordx4 v[224:225], off
	v_lshl_add_u64 v[224:225], s[44:45], 0, v[138:139]
	s_add_i32 m0, s43, 0xe000
	s_nop 0
	global_load_lds_dwordx4 v[224:225], off
	s_waitcnt vmcnt(8)
	s_waitcnt lgkmcnt(0)
	s_barrier
	s_waitcnt lgkmcnt(0)
	v_mfma_f32_16x16x32_bf16 v[124:127], v[144:147], v[190:193], v[124:127]
	v_mfma_f32_16x16x32_bf16 v[120:123], v[166:169], v[190:193], v[120:123]
	v_mfma_f32_16x16x32_bf16 v[108:111], v[144:147], v[200:203], v[108:111]
	v_mfma_f32_16x16x32_bf16 v[104:107], v[166:169], v[200:203], v[104:107]
	v_mfma_f32_16x16x32_bf16 v[92:95], v[144:147], v[208:211], v[92:95]
	v_mfma_f32_16x16x32_bf16 v[88:91], v[166:169], v[208:211], v[88:91]
	v_mfma_f32_16x16x32_bf16 v[76:79], v[144:147], v[216:219], v[76:79]
	v_mfma_f32_16x16x32_bf16 v[72:75], v[166:169], v[216:219], v[72:75]
	v_mfma_f32_16x16x32_bf16 v[124:127], v[162:165], v[194:197], v[124:127]
	v_mfma_f32_16x16x32_bf16 v[120:123], v[170:173], v[194:197], v[120:123]
	v_mfma_f32_16x16x32_bf16 v[108:111], v[162:165], v[204:207], v[108:111]
	v_mfma_f32_16x16x32_bf16 v[104:107], v[170:173], v[204:207], v[104:107]
	v_mfma_f32_16x16x32_bf16 v[92:95], v[162:165], v[212:215], v[92:95]
	v_mfma_f32_16x16x32_bf16 v[88:91], v[170:173], v[212:215], v[88:91]
	v_mfma_f32_16x16x32_bf16 v[76:79], v[162:165], v[220:223], v[76:79]
	v_mfma_f32_16x16x32_bf16 v[72:75], v[170:173], v[220:223], v[72:75]
	v_mfma_f32_16x16x32_bf16 v[116:119], v[174:177], v[190:193], v[116:119]
	v_mfma_f32_16x16x32_bf16 v[112:115], v[182:185], v[190:193], v[112:115]
	v_mfma_f32_16x16x32_bf16 v[100:103], v[174:177], v[200:203], v[100:103]
	v_mfma_f32_16x16x32_bf16 v[96:99], v[182:185], v[200:203], v[96:99]
	v_mfma_f32_16x16x32_bf16 v[84:87], v[174:177], v[208:211], v[84:87]
	v_mfma_f32_16x16x32_bf16 v[80:83], v[182:185], v[208:211], v[80:83]
	v_mfma_f32_16x16x32_bf16 v[68:71], v[174:177], v[216:219], v[68:71]
	v_mfma_f32_16x16x32_bf16 v[64:67], v[182:185], v[216:219], v[64:67]
	v_mfma_f32_16x16x32_bf16 v[116:119], v[178:181], v[194:197], v[116:119]
	v_mfma_f32_16x16x32_bf16 v[112:115], v[186:189], v[194:197], v[112:115]
	v_mfma_f32_16x16x32_bf16 v[100:103], v[178:181], v[204:207], v[100:103]
	v_mfma_f32_16x16x32_bf16 v[96:99], v[186:189], v[204:207], v[96:99]
	v_mfma_f32_16x16x32_bf16 v[84:87], v[178:181], v[212:215], v[84:87]
	v_mfma_f32_16x16x32_bf16 v[80:83], v[186:189], v[212:215], v[80:83]
	v_mfma_f32_16x16x32_bf16 v[68:71], v[178:181], v[220:223], v[68:71]
	v_mfma_f32_16x16x32_bf16 v[64:67], v[186:189], v[220:223], v[64:67]
	s_barrier
	s_add_i32 s67, s61, s52
	v_lshl_add_u64 v[224:225], s[46:47], 0, v[130:131]
	s_mov_b32 m0, s67
	ds_read_b128 v[190:193], v161 offset:16384
	ds_read_b128 v[194:197], v161 offset:17408
	ds_read_b128 v[200:203], v161 offset:18432
	ds_read_b128 v[204:207], v161 offset:19456
	ds_read_b128 v[208:211], v161 offset:20480
	ds_read_b128 v[212:215], v161 offset:21504
	ds_read_b128 v[216:219], v161 offset:22528
	ds_read_b128 v[220:223], v161 offset:23552
	global_load_lds_dwordx4 v[224:225], off
	s_add_i32 m0, s67, 0x2000
	s_add_u32 s70, s46, 0x20000
	v_lshl_add_u64 v[226:227], s[46:47], 0, v[134:135]
	s_addc_u32 s71, s47, 0
	s_add_i32 s67, s62, s52
	global_load_lds_dwordx4 v[226:227], off
	v_lshl_add_u64 v[228:229], s[70:71], 0, v[130:131]
	s_mov_b32 m0, s67
	v_lshl_add_u64 v[230:231], s[48:49], 0, v[132:133]
	global_load_lds_dwordx4 v[228:229], off
	v_lshl_add_u64 v[228:229], s[70:71], 0, v[134:135]
	s_add_i32 m0, s67, 0x2000
	s_nop 0
	global_load_lds_dwordx4 v[228:229], off
	v_lshl_add_u64 v[228:229], s[48:49], 0, v[128:129]
	s_mov_b32 m0, s43
	s_nop 0
	global_load_lds_dwordx4 v[228:229], off
	s_mov_b32 m0, s53
	s_nop 0
	global_load_lds_dwordx4 v[230:231], off
	s_waitcnt vmcnt(8)
	s_waitcnt lgkmcnt(0)
	s_barrier
	s_waitcnt lgkmcnt(0)
	v_mfma_f32_16x16x32_bf16 v[60:63], v[144:147], v[190:193], v[60:63]
	v_mfma_f32_16x16x32_bf16 v[56:59], v[166:169], v[190:193], v[56:59]
	v_mfma_f32_16x16x32_bf16 v[44:47], v[144:147], v[200:203], v[44:47]
	v_mfma_f32_16x16x32_bf16 v[40:43], v[166:169], v[200:203], v[40:43]
	v_mfma_f32_16x16x32_bf16 v[28:31], v[144:147], v[208:211], v[28:31]
	v_mfma_f32_16x16x32_bf16 v[24:27], v[166:169], v[208:211], v[24:27]
	v_mfma_f32_16x16x32_bf16 v[12:15], v[144:147], v[216:219], v[12:15]
	v_mfma_f32_16x16x32_bf16 v[8:11], v[166:169], v[216:219], v[8:11]
	v_mfma_f32_16x16x32_bf16 v[60:63], v[162:165], v[194:197], v[60:63]
	v_mfma_f32_16x16x32_bf16 v[56:59], v[170:173], v[194:197], v[56:59]
	v_mfma_f32_16x16x32_bf16 v[44:47], v[162:165], v[204:207], v[44:47]
	v_mfma_f32_16x16x32_bf16 v[40:43], v[170:173], v[204:207], v[40:43]
	v_mfma_f32_16x16x32_bf16 v[28:31], v[162:165], v[212:215], v[28:31]
	v_mfma_f32_16x16x32_bf16 v[24:27], v[170:173], v[212:215], v[24:27]
	v_mfma_f32_16x16x32_bf16 v[12:15], v[162:165], v[220:223], v[12:15]
	v_mfma_f32_16x16x32_bf16 v[8:11], v[170:173], v[220:223], v[8:11]
	v_mfma_f32_16x16x32_bf16 v[52:55], v[174:177], v[190:193], v[52:55]
	v_mfma_f32_16x16x32_bf16 v[48:51], v[182:185], v[190:193], v[48:51]
	v_mfma_f32_16x16x32_bf16 v[36:39], v[174:177], v[200:203], v[36:39]
	v_mfma_f32_16x16x32_bf16 v[32:35], v[182:185], v[200:203], v[32:35]
	v_mfma_f32_16x16x32_bf16 v[20:23], v[174:177], v[208:211], v[20:23]
	v_mfma_f32_16x16x32_bf16 v[16:19], v[182:185], v[208:211], v[16:19]
	v_mfma_f32_16x16x32_bf16 v[4:7], v[174:177], v[216:219], v[4:7]
	v_mfma_f32_16x16x32_bf16 v[0:3], v[182:185], v[216:219], v[0:3]
	v_mfma_f32_16x16x32_bf16 v[52:55], v[178:181], v[194:197], v[52:55]
	v_mfma_f32_16x16x32_bf16 v[48:51], v[186:189], v[194:197], v[48:51]
	v_mfma_f32_16x16x32_bf16 v[36:39], v[178:181], v[204:207], v[36:39]
	v_mfma_f32_16x16x32_bf16 v[32:35], v[186:189], v[204:207], v[32:35]
	v_mfma_f32_16x16x32_bf16 v[20:23], v[178:181], v[212:215], v[20:23]
	v_mfma_f32_16x16x32_bf16 v[16:19], v[186:189], v[212:215], v[16:19]
	v_mfma_f32_16x16x32_bf16 v[4:7], v[178:181], v[220:223], v[4:7]
	v_mfma_f32_16x16x32_bf16 v[0:3], v[186:189], v[220:223], v[0:3]
	s_barrier
	s_add_i32 s67, 0, 0x18000
	s_add_i32 s70, 0, 0x1c000
	v_add_u32_e32 v170, s67, v157
	v_add_u32_e32 v186, s70, v157
	ds_read_b128 v[144:147], v170
	ds_read_b128 v[162:165], v170 offset:1024
	ds_read_b128 v[166:169], v170 offset:2048
	ds_read_b128 v[170:173], v170 offset:3072
	ds_read_b128 v[174:177], v186
	ds_read_b128 v[178:181], v186 offset:1024
	ds_read_b128 v[182:185], v186 offset:2048
	ds_read_b128 v[186:189], v186 offset:3072
	s_add_u32 s48, s48, 0x20000
	s_addc_u32 s49, s49, 0
	s_mov_b32 m0, s54
	v_lshl_add_u64 v[232:233], s[48:49], 0, v[128:129]
	ds_read_b128 v[190:193], v161 offset:32768
	ds_read_b128 v[194:197], v161 offset:33792
	ds_read_b128 v[200:203], v161 offset:34816
	ds_read_b128 v[204:207], v161 offset:35840
	ds_read_b128 v[208:211], v161 offset:36864
	ds_read_b128 v[212:215], v161 offset:37888
	ds_read_b128 v[216:219], v161 offset:38912
	ds_read_b128 v[220:223], v161 offset:39936
	global_load_lds_dwordx4 v[232:233], off
	v_lshl_add_u64 v[232:233], s[48:49], 0, v[132:133]
	s_mov_b32 m0, s55
	s_nop 0
	global_load_lds_dwordx4 v[232:233], off
	s_waitcnt vmcnt(8)
	s_waitcnt lgkmcnt(0)
	s_barrier
	s_waitcnt lgkmcnt(0)
	v_mfma_f32_16x16x32_bf16 v[124:127], v[144:147], v[190:193], v[124:127]
	v_mfma_f32_16x16x32_bf16 v[120:123], v[166:169], v[190:193], v[120:123]
	v_mfma_f32_16x16x32_bf16 v[108:111], v[144:147], v[200:203], v[108:111]
	v_mfma_f32_16x16x32_bf16 v[104:107], v[166:169], v[200:203], v[104:107]
	v_mfma_f32_16x16x32_bf16 v[92:95], v[144:147], v[208:211], v[92:95]
	v_mfma_f32_16x16x32_bf16 v[88:91], v[166:169], v[208:211], v[88:91]
	v_mfma_f32_16x16x32_bf16 v[76:79], v[144:147], v[216:219], v[76:79]
	v_mfma_f32_16x16x32_bf16 v[72:75], v[166:169], v[216:219], v[72:75]
	v_mfma_f32_16x16x32_bf16 v[124:127], v[162:165], v[194:197], v[124:127]
	v_mfma_f32_16x16x32_bf16 v[120:123], v[170:173], v[194:197], v[120:123]
	v_mfma_f32_16x16x32_bf16 v[108:111], v[162:165], v[204:207], v[108:111]
	v_mfma_f32_16x16x32_bf16 v[104:107], v[170:173], v[204:207], v[104:107]
	v_mfma_f32_16x16x32_bf16 v[92:95], v[162:165], v[212:215], v[92:95]
	v_mfma_f32_16x16x32_bf16 v[88:91], v[170:173], v[212:215], v[88:91]
	v_mfma_f32_16x16x32_bf16 v[76:79], v[162:165], v[220:223], v[76:79]
	v_mfma_f32_16x16x32_bf16 v[72:75], v[170:173], v[220:223], v[72:75]
	v_mfma_f32_16x16x32_bf16 v[116:119], v[174:177], v[190:193], v[116:119]
	v_mfma_f32_16x16x32_bf16 v[112:115], v[182:185], v[190:193], v[112:115]
	v_mfma_f32_16x16x32_bf16 v[100:103], v[174:177], v[200:203], v[100:103]
	v_mfma_f32_16x16x32_bf16 v[96:99], v[182:185], v[200:203], v[96:99]
	v_mfma_f32_16x16x32_bf16 v[84:87], v[174:177], v[208:211], v[84:87]
	v_mfma_f32_16x16x32_bf16 v[80:83], v[182:185], v[208:211], v[80:83]
	v_mfma_f32_16x16x32_bf16 v[68:71], v[174:177], v[216:219], v[68:71]
	v_mfma_f32_16x16x32_bf16 v[64:67], v[182:185], v[216:219], v[64:67]
	v_mfma_f32_16x16x32_bf16 v[116:119], v[178:181], v[194:197], v[116:119]
	v_mfma_f32_16x16x32_bf16 v[112:115], v[186:189], v[194:197], v[112:115]
	v_mfma_f32_16x16x32_bf16 v[100:103], v[178:181], v[204:207], v[100:103]
	v_mfma_f32_16x16x32_bf16 v[96:99], v[186:189], v[204:207], v[96:99]
	v_mfma_f32_16x16x32_bf16 v[84:87], v[178:181], v[212:215], v[84:87]
	v_mfma_f32_16x16x32_bf16 v[80:83], v[186:189], v[212:215], v[80:83]
	v_mfma_f32_16x16x32_bf16 v[68:71], v[178:181], v[220:223], v[68:71]
	v_mfma_f32_16x16x32_bf16 v[64:67], v[186:189], v[220:223], v[64:67]
	s_barrier
	s_add_i32 s48, s67, s52
	v_lshl_add_u64 v[224:225], v[224:225], 0, s[8:9]
	s_mov_b32 m0, s48
	ds_read_b128 v[190:193], v161 offset:49152
	ds_read_b128 v[194:197], v161 offset:50176
	ds_read_b128 v[200:203], v161 offset:51200
	ds_read_b128 v[204:207], v161 offset:52224
	ds_read_b128 v[208:211], v161 offset:53248
	ds_read_b128 v[212:215], v161 offset:54272
	ds_read_b128 v[216:219], v161 offset:55296
	ds_read_b128 v[220:223], v161 offset:56320
	global_load_lds_dwordx4 v[224:225], off
	s_add_i32 m0, s48, 0x2000
	s_add_u32 s46, s46, 0x20080
	v_lshl_add_u64 v[224:225], v[226:227], 0, s[8:9]
	s_addc_u32 s47, s47, 0
	s_add_i32 s48, s70, s52
	global_load_lds_dwordx4 v[224:225], off
	v_lshl_add_u64 v[224:225], s[46:47], 0, v[130:131]
	s_mov_b32 m0, s48
	s_nop 0
	global_load_lds_dwordx4 v[224:225], off
	v_lshl_add_u64 v[224:225], s[46:47], 0, v[134:135]
	s_add_i32 m0, s48, 0x2000
	s_nop 0
	global_load_lds_dwordx4 v[224:225], off
	v_lshl_add_u64 v[224:225], v[228:229], 0, s[8:9]
	s_mov_b32 m0, s57
	s_nop 0
	global_load_lds_dwordx4 v[224:225], off
	v_lshl_add_u64 v[224:225], v[230:231], 0, s[8:9]
	s_mov_b32 m0, s58
	s_nop 0
	global_load_lds_dwordx4 v[224:225], off
	s_waitcnt vmcnt(8)
	s_waitcnt lgkmcnt(0)
	s_barrier
	s_waitcnt lgkmcnt(0)
	v_mfma_f32_16x16x32_bf16 v[60:63], v[144:147], v[190:193], v[60:63]
	v_mfma_f32_16x16x32_bf16 v[56:59], v[166:169], v[190:193], v[56:59]
	v_mfma_f32_16x16x32_bf16 v[44:47], v[144:147], v[200:203], v[44:47]
	v_mfma_f32_16x16x32_bf16 v[40:43], v[166:169], v[200:203], v[40:43]
	v_mfma_f32_16x16x32_bf16 v[28:31], v[144:147], v[208:211], v[28:31]
	v_mfma_f32_16x16x32_bf16 v[24:27], v[166:169], v[208:211], v[24:27]
	v_mfma_f32_16x16x32_bf16 v[12:15], v[144:147], v[216:219], v[12:15]
	v_mfma_f32_16x16x32_bf16 v[8:11], v[166:169], v[216:219], v[8:11]
	v_mfma_f32_16x16x32_bf16 v[60:63], v[162:165], v[194:197], v[60:63]
	v_mfma_f32_16x16x32_bf16 v[56:59], v[170:173], v[194:197], v[56:59]
	v_mfma_f32_16x16x32_bf16 v[44:47], v[162:165], v[204:207], v[44:47]
	v_mfma_f32_16x16x32_bf16 v[40:43], v[170:173], v[204:207], v[40:43]
	v_mfma_f32_16x16x32_bf16 v[28:31], v[162:165], v[212:215], v[28:31]
	v_mfma_f32_16x16x32_bf16 v[24:27], v[170:173], v[212:215], v[24:27]
	v_mfma_f32_16x16x32_bf16 v[12:15], v[162:165], v[220:223], v[12:15]
	v_mfma_f32_16x16x32_bf16 v[8:11], v[170:173], v[220:223], v[8:11]
	v_mfma_f32_16x16x32_bf16 v[52:55], v[174:177], v[190:193], v[52:55]
	v_mfma_f32_16x16x32_bf16 v[48:51], v[182:185], v[190:193], v[48:51]
	v_mfma_f32_16x16x32_bf16 v[36:39], v[174:177], v[200:203], v[36:39]
	v_mfma_f32_16x16x32_bf16 v[32:35], v[182:185], v[200:203], v[32:35]
	v_mfma_f32_16x16x32_bf16 v[20:23], v[174:177], v[208:211], v[20:23]
	v_mfma_f32_16x16x32_bf16 v[16:19], v[182:185], v[208:211], v[16:19]
	v_mfma_f32_16x16x32_bf16 v[4:7], v[174:177], v[216:219], v[4:7]
	v_mfma_f32_16x16x32_bf16 v[0:3], v[182:185], v[216:219], v[0:3]
	v_mfma_f32_16x16x32_bf16 v[52:55], v[178:181], v[194:197], v[52:55]
	v_mfma_f32_16x16x32_bf16 v[48:51], v[186:189], v[194:197], v[48:51]
	v_mfma_f32_16x16x32_bf16 v[36:39], v[178:181], v[204:207], v[36:39]
	v_mfma_f32_16x16x32_bf16 v[32:35], v[186:189], v[204:207], v[32:35]
	v_mfma_f32_16x16x32_bf16 v[20:23], v[178:181], v[212:215], v[20:23]
	v_mfma_f32_16x16x32_bf16 v[16:19], v[186:189], v[212:215], v[16:19]
	v_mfma_f32_16x16x32_bf16 v[4:7], v[178:181], v[220:223], v[4:7]
	v_mfma_f32_16x16x32_bf16 v[0:3], v[186:189], v[220:223], v[0:3]
	s_barrier
	s_add_i32 s66, s66, 2
	s_add_u32 s44, s44, 0x100
	s_addc_u32 s45, s45, 0
	s_add_u32 s64, s64, 0x100
	s_addc_u32 s65, s65, 0
	s_cmp_gt_u32 s66, 5
	s_cbranch_scc0 .LBB0_1471
	s_and_b64 vcc, exec, s[12:13]
	s_cbranch_vccz .LBB0_1474
	s_barrier

.LBB0_1495:
	ds_read_b128 v[144:147], v153
	ds_read_b128 v[156:159], v153 offset:1024
	ds_read_b128 v[160:163], v153 offset:2048
	ds_read_b128 v[164:167], v153 offset:3072
	ds_read_b128 v[168:171], v154
	ds_read_b128 v[172:175], v154 offset:1024
	ds_read_b128 v[176:179], v154 offset:2048
	ds_read_b128 v[180:183], v154 offset:3072
	s_add_u32 s48, s46, 0xfffe0080
	s_addc_u32 s49, s47, -1
	s_cmp_eq_u32 s66, 4
	s_cselect_b32 s51, s10, s49
	s_cselect_b32 s50, s11, s48
	s_cselect_b32 s49, s21, s65
	s_cselect_b32 s48, s25, s64
	v_lshl_add_u64 v[148:149], s[46:47], 0, v[136:137]
	s_add_i32 m0, s45, 0xc000
	ds_read_b128 v[184:187], v155
	ds_read_b128 v[188:191], v155 offset:1024
	ds_read_b128 v[192:195], v155 offset:2048
	ds_read_b128 v[200:203], v155 offset:3072
	ds_read_b128 v[204:207], v155 offset:4096
	ds_read_b128 v[208:211], v155 offset:5120
	ds_read_b128 v[212:215], v155 offset:6144
	ds_read_b128 v[216:219], v155 offset:7168
	global_load_lds_dwordx4 v[148:149], off
	v_lshl_add_u64 v[148:149], s[46:47], 0, v[138:139]
	s_add_i32 m0, s45, 0xe000
	s_nop 0
	global_load_lds_dwordx4 v[148:149], off
	s_waitcnt vmcnt(8)
	s_waitcnt lgkmcnt(0)
	s_barrier
	s_waitcnt lgkmcnt(0)
	v_mfma_f32_16x16x32_bf16 v[124:127], v[144:147], v[184:187], v[124:127]
	v_mfma_f32_16x16x32_bf16 v[120:123], v[160:163], v[184:187], v[120:123]
	v_mfma_f32_16x16x32_bf16 v[108:111], v[144:147], v[192:195], v[108:111]
	v_mfma_f32_16x16x32_bf16 v[104:107], v[160:163], v[192:195], v[104:107]
	v_mfma_f32_16x16x32_bf16 v[92:95], v[144:147], v[204:207], v[92:95]
	v_mfma_f32_16x16x32_bf16 v[88:91], v[160:163], v[204:207], v[88:91]
	v_mfma_f32_16x16x32_bf16 v[76:79], v[144:147], v[212:215], v[76:79]
	v_mfma_f32_16x16x32_bf16 v[72:75], v[160:163], v[212:215], v[72:75]
	v_mfma_f32_16x16x32_bf16 v[124:127], v[156:159], v[188:191], v[124:127]
	v_mfma_f32_16x16x32_bf16 v[120:123], v[164:167], v[188:191], v[120:123]
	v_mfma_f32_16x16x32_bf16 v[108:111], v[156:159], v[200:203], v[108:111]
	v_mfma_f32_16x16x32_bf16 v[104:107], v[164:167], v[200:203], v[104:107]
	v_mfma_f32_16x16x32_bf16 v[92:95], v[156:159], v[208:211], v[92:95]
	v_mfma_f32_16x16x32_bf16 v[88:91], v[164:167], v[208:211], v[88:91]
	v_mfma_f32_16x16x32_bf16 v[76:79], v[156:159], v[216:219], v[76:79]
	v_mfma_f32_16x16x32_bf16 v[72:75], v[164:167], v[216:219], v[72:75]
	v_mfma_f32_16x16x32_bf16 v[116:119], v[168:171], v[184:187], v[116:119]
	v_mfma_f32_16x16x32_bf16 v[112:115], v[176:179], v[184:187], v[112:115]
	v_mfma_f32_16x16x32_bf16 v[100:103], v[168:171], v[192:195], v[100:103]
	v_mfma_f32_16x16x32_bf16 v[96:99], v[176:179], v[192:195], v[96:99]
	v_mfma_f32_16x16x32_bf16 v[84:87], v[168:171], v[204:207], v[84:87]
	v_mfma_f32_16x16x32_bf16 v[80:83], v[176:179], v[204:207], v[80:83]
	v_mfma_f32_16x16x32_bf16 v[68:71], v[168:171], v[212:215], v[68:71]
	v_mfma_f32_16x16x32_bf16 v[64:67], v[176:179], v[212:215], v[64:67]
	v_mfma_f32_16x16x32_bf16 v[116:119], v[172:175], v[188:191], v[116:119]
	v_mfma_f32_16x16x32_bf16 v[112:115], v[180:183], v[188:191], v[112:115]
	v_mfma_f32_16x16x32_bf16 v[100:103], v[172:175], v[200:203], v[100:103]
	v_mfma_f32_16x16x32_bf16 v[96:99], v[180:183], v[200:203], v[96:99]
	v_mfma_f32_16x16x32_bf16 v[84:87], v[172:175], v[208:211], v[84:87]
	v_mfma_f32_16x16x32_bf16 v[80:83], v[180:183], v[208:211], v[80:83]
	v_mfma_f32_16x16x32_bf16 v[68:71], v[172:175], v[216:219], v[68:71]
	v_mfma_f32_16x16x32_bf16 v[64:67], v[180:183], v[216:219], v[64:67]
	s_barrier
	s_add_i32 s67, s61, s52
	v_lshl_add_u64 v[148:149], s[48:49], 0, v[130:131]
	s_mov_b32 m0, s67
	ds_read_b128 v[184:187], v155 offset:16384
	ds_read_b128 v[188:191], v155 offset:17408
	ds_read_b128 v[192:195], v155 offset:18432
	ds_read_b128 v[200:203], v155 offset:19456
	ds_read_b128 v[204:207], v155 offset:20480
	ds_read_b128 v[208:211], v155 offset:21504
	ds_read_b128 v[212:215], v155 offset:22528
	ds_read_b128 v[216:219], v155 offset:23552
	global_load_lds_dwordx4 v[148:149], off
	s_add_i32 m0, s67, 0x2000
	s_add_u32 s70, s48, 0x20000
	v_lshl_add_u64 v[196:197], s[48:49], 0, v[134:135]
	s_addc_u32 s71, s49, 0
	s_add_i32 s67, s62, s52
	global_load_lds_dwordx4 v[196:197], off
	v_lshl_add_u64 v[220:221], s[70:71], 0, v[130:131]
	s_mov_b32 m0, s67
	v_lshl_add_u64 v[222:223], s[50:51], 0, v[132:133]
	global_load_lds_dwordx4 v[220:221], off
	v_lshl_add_u64 v[220:221], s[70:71], 0, v[134:135]
	s_add_i32 m0, s67, 0x2000
	s_nop 0
	global_load_lds_dwordx4 v[220:221], off
	v_lshl_add_u64 v[220:221], s[50:51], 0, v[128:129]
	s_mov_b32 m0, s45
	s_nop 0
	global_load_lds_dwordx4 v[220:221], off
	s_mov_b32 m0, s53
	s_nop 0
	global_load_lds_dwordx4 v[222:223], off
	s_waitcnt vmcnt(8)
	s_waitcnt lgkmcnt(0)
	s_barrier
	s_waitcnt lgkmcnt(0)
	v_mfma_f32_16x16x32_bf16 v[60:63], v[144:147], v[184:187], v[60:63]
	v_mfma_f32_16x16x32_bf16 v[56:59], v[160:163], v[184:187], v[56:59]
	v_mfma_f32_16x16x32_bf16 v[44:47], v[144:147], v[192:195], v[44:47]
	v_mfma_f32_16x16x32_bf16 v[40:43], v[160:163], v[192:195], v[40:43]
	v_mfma_f32_16x16x32_bf16 v[28:31], v[144:147], v[204:207], v[28:31]
	v_mfma_f32_16x16x32_bf16 v[24:27], v[160:163], v[204:207], v[24:27]
	v_mfma_f32_16x16x32_bf16 v[12:15], v[144:147], v[212:215], v[12:15]
	v_mfma_f32_16x16x32_bf16 v[8:11], v[160:163], v[212:215], v[8:11]
	v_mfma_f32_16x16x32_bf16 v[60:63], v[156:159], v[188:191], v[60:63]
	v_mfma_f32_16x16x32_bf16 v[56:59], v[164:167], v[188:191], v[56:59]
	v_mfma_f32_16x16x32_bf16 v[44:47], v[156:159], v[200:203], v[44:47]
	v_mfma_f32_16x16x32_bf16 v[40:43], v[164:167], v[200:203], v[40:43]
	v_mfma_f32_16x16x32_bf16 v[28:31], v[156:159], v[208:211], v[28:31]
	v_mfma_f32_16x16x32_bf16 v[24:27], v[164:167], v[208:211], v[24:27]
	v_mfma_f32_16x16x32_bf16 v[12:15], v[156:159], v[216:219], v[12:15]
	v_mfma_f32_16x16x32_bf16 v[8:11], v[164:167], v[216:219], v[8:11]
	v_mfma_f32_16x16x32_bf16 v[52:55], v[168:171], v[184:187], v[52:55]
	v_mfma_f32_16x16x32_bf16 v[48:51], v[176:179], v[184:187], v[48:51]
	v_mfma_f32_16x16x32_bf16 v[36:39], v[168:171], v[192:195], v[36:39]
	v_mfma_f32_16x16x32_bf16 v[32:35], v[176:179], v[192:195], v[32:35]
	v_mfma_f32_16x16x32_bf16 v[20:23], v[168:171], v[204:207], v[20:23]
	v_mfma_f32_16x16x32_bf16 v[16:19], v[176:179], v[204:207], v[16:19]
	v_mfma_f32_16x16x32_bf16 v[4:7], v[168:171], v[212:215], v[4:7]
	v_mfma_f32_16x16x32_bf16 v[0:3], v[176:179], v[212:215], v[0:3]
	v_mfma_f32_16x16x32_bf16 v[52:55], v[172:175], v[188:191], v[52:55]
	v_mfma_f32_16x16x32_bf16 v[48:51], v[180:183], v[188:191], v[48:51]
	v_mfma_f32_16x16x32_bf16 v[36:39], v[172:175], v[200:203], v[36:39]
	v_mfma_f32_16x16x32_bf16 v[32:35], v[180:183], v[200:203], v[32:35]
	v_mfma_f32_16x16x32_bf16 v[20:23], v[172:175], v[208:211], v[20:23]
	v_mfma_f32_16x16x32_bf16 v[16:19], v[180:183], v[208:211], v[16:19]
	v_mfma_f32_16x16x32_bf16 v[4:7], v[172:175], v[216:219], v[4:7]
	v_mfma_f32_16x16x32_bf16 v[0:3], v[180:183], v[216:219], v[0:3]
	s_barrier
	s_add_i32 s67, 0, 0x18000
	s_add_i32 s70, 0, 0x1c000
	v_add_u32_e32 v164, s67, v151
	v_add_u32_e32 v180, s70, v151
	ds_read_b128 v[144:147], v164
	ds_read_b128 v[156:159], v164 offset:1024
	ds_read_b128 v[160:163], v164 offset:2048
	ds_read_b128 v[164:167], v164 offset:3072
	ds_read_b128 v[168:171], v180
	ds_read_b128 v[172:175], v180 offset:1024
	ds_read_b128 v[176:179], v180 offset:2048
	ds_read_b128 v[180:183], v180 offset:3072
	s_add_u32 s50, s50, 0x20000
	s_addc_u32 s51, s51, 0
	s_mov_b32 m0, s54
	v_lshl_add_u64 v[224:225], s[50:51], 0, v[128:129]
	ds_read_b128 v[184:187], v155 offset:32768
	ds_read_b128 v[188:191], v155 offset:33792
	ds_read_b128 v[192:195], v155 offset:34816
	ds_read_b128 v[200:203], v155 offset:35840
	ds_read_b128 v[204:207], v155 offset:36864
	ds_read_b128 v[208:211], v155 offset:37888
	ds_read_b128 v[212:215], v155 offset:38912
	ds_read_b128 v[216:219], v155 offset:39936
	global_load_lds_dwordx4 v[224:225], off
	v_lshl_add_u64 v[224:225], s[50:51], 0, v[132:133]
	s_mov_b32 m0, s55
	s_nop 0
	global_load_lds_dwordx4 v[224:225], off
	s_waitcnt vmcnt(8)
	s_waitcnt lgkmcnt(0)
	s_barrier
	s_waitcnt lgkmcnt(0)
	v_mfma_f32_16x16x32_bf16 v[124:127], v[144:147], v[184:187], v[124:127]
	v_mfma_f32_16x16x32_bf16 v[120:123], v[160:163], v[184:187], v[120:123]
	v_mfma_f32_16x16x32_bf16 v[108:111], v[144:147], v[192:195], v[108:111]
	v_mfma_f32_16x16x32_bf16 v[104:107], v[160:163], v[192:195], v[104:107]
	v_mfma_f32_16x16x32_bf16 v[92:95], v[144:147], v[204:207], v[92:95]
	v_mfma_f32_16x16x32_bf16 v[88:91], v[160:163], v[204:207], v[88:91]
	v_mfma_f32_16x16x32_bf16 v[76:79], v[144:147], v[212:215], v[76:79]
	v_mfma_f32_16x16x32_bf16 v[72:75], v[160:163], v[212:215], v[72:75]
	v_mfma_f32_16x16x32_bf16 v[124:127], v[156:159], v[188:191], v[124:127]
	v_mfma_f32_16x16x32_bf16 v[120:123], v[164:167], v[188:191], v[120:123]
	v_mfma_f32_16x16x32_bf16 v[108:111], v[156:159], v[200:203], v[108:111]
	v_mfma_f32_16x16x32_bf16 v[104:107], v[164:167], v[200:203], v[104:107]
	v_mfma_f32_16x16x32_bf16 v[92:95], v[156:159], v[208:211], v[92:95]
	v_mfma_f32_16x16x32_bf16 v[88:91], v[164:167], v[208:211], v[88:91]
	v_mfma_f32_16x16x32_bf16 v[76:79], v[156:159], v[216:219], v[76:79]
	v_mfma_f32_16x16x32_bf16 v[72:75], v[164:167], v[216:219], v[72:75]
	v_mfma_f32_16x16x32_bf16 v[116:119], v[168:171], v[184:187], v[116:119]
	v_mfma_f32_16x16x32_bf16 v[112:115], v[176:179], v[184:187], v[112:115]
	v_mfma_f32_16x16x32_bf16 v[100:103], v[168:171], v[192:195], v[100:103]
	v_mfma_f32_16x16x32_bf16 v[96:99], v[176:179], v[192:195], v[96:99]
	v_mfma_f32_16x16x32_bf16 v[84:87], v[168:171], v[204:207], v[84:87]
	v_mfma_f32_16x16x32_bf16 v[80:83], v[176:179], v[204:207], v[80:83]
	v_mfma_f32_16x16x32_bf16 v[68:71], v[168:171], v[212:215], v[68:71]
	v_mfma_f32_16x16x32_bf16 v[64:67], v[176:179], v[212:215], v[64:67]
	v_mfma_f32_16x16x32_bf16 v[116:119], v[172:175], v[188:191], v[116:119]
	v_mfma_f32_16x16x32_bf16 v[112:115], v[180:183], v[188:191], v[112:115]
	v_mfma_f32_16x16x32_bf16 v[100:103], v[172:175], v[200:203], v[100:103]
	v_mfma_f32_16x16x32_bf16 v[96:99], v[180:183], v[200:203], v[96:99]
	v_mfma_f32_16x16x32_bf16 v[84:87], v[172:175], v[208:211], v[84:87]
	v_mfma_f32_16x16x32_bf16 v[80:83], v[180:183], v[208:211], v[80:83]
	v_mfma_f32_16x16x32_bf16 v[68:71], v[172:175], v[216:219], v[68:71]
	v_mfma_f32_16x16x32_bf16 v[64:67], v[180:183], v[216:219], v[64:67]
	s_barrier
	s_add_i32 s50, s67, s52
	v_lshl_add_u64 v[148:149], v[148:149], 0, s[6:7]
	s_mov_b32 m0, s50
	ds_read_b128 v[184:187], v155 offset:49152
	ds_read_b128 v[188:191], v155 offset:50176
	ds_read_b128 v[192:195], v155 offset:51200
	ds_read_b128 v[200:203], v155 offset:52224
	ds_read_b128 v[204:207], v155 offset:53248
	ds_read_b128 v[208:211], v155 offset:54272
	ds_read_b128 v[212:215], v155 offset:55296
	ds_read_b128 v[216:219], v155 offset:56320
	global_load_lds_dwordx4 v[148:149], off
	s_add_i32 m0, s50, 0x2000
	s_add_u32 s48, s48, 0x20080
	v_lshl_add_u64 v[148:149], v[196:197], 0, s[6:7]
	s_addc_u32 s49, s49, 0
	s_add_i32 s50, s70, s52
	global_load_lds_dwordx4 v[148:149], off
	v_lshl_add_u64 v[148:149], s[48:49], 0, v[130:131]
	s_mov_b32 m0, s50
	s_nop 0
	global_load_lds_dwordx4 v[148:149], off
	v_lshl_add_u64 v[148:149], s[48:49], 0, v[134:135]
	s_add_i32 m0, s50, 0x2000
	s_nop 0
	global_load_lds_dwordx4 v[148:149], off
	v_lshl_add_u64 v[148:149], v[220:221], 0, s[6:7]
	s_mov_b32 m0, s57
	s_nop 0
	global_load_lds_dwordx4 v[148:149], off
	v_lshl_add_u64 v[148:149], v[222:223], 0, s[6:7]
	s_mov_b32 m0, s58
	s_nop 0
	global_load_lds_dwordx4 v[148:149], off
	s_waitcnt vmcnt(8)
	s_waitcnt lgkmcnt(0)
	s_barrier
	s_waitcnt lgkmcnt(0)
	v_mfma_f32_16x16x32_bf16 v[60:63], v[144:147], v[184:187], v[60:63]
	v_mfma_f32_16x16x32_bf16 v[56:59], v[160:163], v[184:187], v[56:59]
	v_mfma_f32_16x16x32_bf16 v[44:47], v[144:147], v[192:195], v[44:47]
	v_mfma_f32_16x16x32_bf16 v[40:43], v[160:163], v[192:195], v[40:43]
	v_mfma_f32_16x16x32_bf16 v[28:31], v[144:147], v[204:207], v[28:31]
	v_mfma_f32_16x16x32_bf16 v[24:27], v[160:163], v[204:207], v[24:27]
	v_mfma_f32_16x16x32_bf16 v[12:15], v[144:147], v[212:215], v[12:15]
	v_mfma_f32_16x16x32_bf16 v[8:11], v[160:163], v[212:215], v[8:11]
	v_mfma_f32_16x16x32_bf16 v[60:63], v[156:159], v[188:191], v[60:63]
	v_mfma_f32_16x16x32_bf16 v[56:59], v[164:167], v[188:191], v[56:59]
	v_mfma_f32_16x16x32_bf16 v[44:47], v[156:159], v[200:203], v[44:47]
	v_mfma_f32_16x16x32_bf16 v[40:43], v[164:167], v[200:203], v[40:43]
	v_mfma_f32_16x16x32_bf16 v[28:31], v[156:159], v[208:211], v[28:31]
	v_mfma_f32_16x16x32_bf16 v[24:27], v[164:167], v[208:211], v[24:27]
	v_mfma_f32_16x16x32_bf16 v[12:15], v[156:159], v[216:219], v[12:15]
	v_mfma_f32_16x16x32_bf16 v[8:11], v[164:167], v[216:219], v[8:11]
	v_mfma_f32_16x16x32_bf16 v[52:55], v[168:171], v[184:187], v[52:55]
	v_mfma_f32_16x16x32_bf16 v[48:51], v[176:179], v[184:187], v[48:51]
	v_mfma_f32_16x16x32_bf16 v[36:39], v[168:171], v[192:195], v[36:39]
	v_mfma_f32_16x16x32_bf16 v[32:35], v[176:179], v[192:195], v[32:35]
	v_mfma_f32_16x16x32_bf16 v[20:23], v[168:171], v[204:207], v[20:23]
	v_mfma_f32_16x16x32_bf16 v[16:19], v[176:179], v[204:207], v[16:19]
	v_mfma_f32_16x16x32_bf16 v[4:7], v[168:171], v[212:215], v[4:7]
	v_mfma_f32_16x16x32_bf16 v[0:3], v[176:179], v[212:215], v[0:3]
	v_mfma_f32_16x16x32_bf16 v[52:55], v[172:175], v[188:191], v[52:55]
	v_mfma_f32_16x16x32_bf16 v[48:51], v[180:183], v[188:191], v[48:51]
	v_mfma_f32_16x16x32_bf16 v[36:39], v[172:175], v[200:203], v[36:39]
	v_mfma_f32_16x16x32_bf16 v[32:35], v[180:183], v[200:203], v[32:35]
	v_mfma_f32_16x16x32_bf16 v[20:23], v[172:175], v[208:211], v[20:23]
	v_mfma_f32_16x16x32_bf16 v[16:19], v[180:183], v[208:211], v[16:19]
	v_mfma_f32_16x16x32_bf16 v[4:7], v[172:175], v[216:219], v[4:7]
	v_mfma_f32_16x16x32_bf16 v[0:3], v[180:183], v[216:219], v[0:3]
	s_barrier
	s_add_i32 s66, s66, 2
	s_add_u32 s46, s46, 0x100
	s_addc_u32 s47, s47, 0
	s_add_u32 s64, s64, 0x100
	s_addc_u32 s65, s65, 0
	s_cmp_gt_u32 s66, 5
	s_cbranch_scc0 .LBB0_1495
	s_and_b64 vcc, exec, s[8:9]
	s_cbranch_vccz .LBB0_1498
	s_barrier

.LBB0_1576:
	ds_read_b128 v[88:91], v175
	ds_read_b128 v[92:95], v175 offset:1024
	ds_read_b128 v[96:99], v175 offset:2048
	ds_read_b128 v[100:103], v175 offset:3072
	ds_read_b128 v[160:163], v176
	ds_read_b128 v[164:167], v176 offset:1024
	ds_read_b128 v[168:171], v176 offset:2048
	ds_read_b128 v[180:183], v176 offset:3072
	s_add_u32 s50, s48, 0xfffc0080
	s_addc_u32 s51, s49, -1
	s_cmp_eq_u32 s76, 12
	s_cselect_b32 s53, s10, s51
	s_cselect_b32 s52, s11, s50
	s_cselect_b32 s51, s21, s75
	s_cselect_b32 s50, s25, s45
	v_lshl_add_u64 v[196:197], s[48:49], 0, v[152:153]
	s_add_i32 m0, s47, 0xc000
	ds_read_b128 v[184:187], v177
	ds_read_b128 v[188:191], v177 offset:1024
	ds_read_b128 v[192:195], v177 offset:2048
	ds_read_b128 v[200:203], v177 offset:3072
	ds_read_b128 v[204:207], v177 offset:4096
	ds_read_b128 v[208:211], v177 offset:5120
	ds_read_b128 v[212:215], v177 offset:6144
	ds_read_b128 v[216:219], v177 offset:7168
	global_load_lds_dwordx4 v[196:197], off
	v_lshl_add_u64 v[196:197], s[48:49], 0, v[154:155]
	s_add_i32 m0, s47, 0xe000
	s_nop 0
	global_load_lds_dwordx4 v[196:197], off
	s_waitcnt vmcnt(8)
	s_waitcnt lgkmcnt(0)
	s_barrier
	s_waitcnt lgkmcnt(0)
	v_mfma_f32_16x16x32_bf16 v[140:143], v[88:91], v[184:187], v[140:143]
	v_mfma_f32_16x16x32_bf16 v[136:139], v[96:99], v[184:187], v[136:139]
	v_mfma_f32_16x16x32_bf16 v[124:127], v[88:91], v[192:195], v[124:127]
	v_mfma_f32_16x16x32_bf16 v[120:123], v[96:99], v[192:195], v[120:123]
	v_mfma_f32_16x16x32_bf16 v[108:111], v[88:91], v[204:207], v[108:111]
	v_mfma_f32_16x16x32_bf16 v[104:107], v[96:99], v[204:207], v[104:107]
	v_mfma_f32_16x16x32_bf16 v[76:79], v[88:91], v[212:215], v[76:79]
	v_mfma_f32_16x16x32_bf16 v[72:75], v[96:99], v[212:215], v[72:75]
	v_mfma_f32_16x16x32_bf16 v[140:143], v[92:95], v[188:191], v[140:143]
	v_mfma_f32_16x16x32_bf16 v[136:139], v[100:103], v[188:191], v[136:139]
	v_mfma_f32_16x16x32_bf16 v[124:127], v[92:95], v[200:203], v[124:127]
	v_mfma_f32_16x16x32_bf16 v[120:123], v[100:103], v[200:203], v[120:123]
	v_mfma_f32_16x16x32_bf16 v[108:111], v[92:95], v[208:211], v[108:111]
	v_mfma_f32_16x16x32_bf16 v[104:107], v[100:103], v[208:211], v[104:107]
	v_mfma_f32_16x16x32_bf16 v[76:79], v[92:95], v[216:219], v[76:79]
	v_mfma_f32_16x16x32_bf16 v[72:75], v[100:103], v[216:219], v[72:75]
	v_mfma_f32_16x16x32_bf16 v[132:135], v[160:163], v[184:187], v[132:135]
	v_mfma_f32_16x16x32_bf16 v[128:131], v[168:171], v[184:187], v[128:131]
	v_mfma_f32_16x16x32_bf16 v[116:119], v[160:163], v[192:195], v[116:119]
	v_mfma_f32_16x16x32_bf16 v[112:115], v[168:171], v[192:195], v[112:115]
	v_mfma_f32_16x16x32_bf16 v[84:87], v[160:163], v[204:207], v[84:87]
	v_mfma_f32_16x16x32_bf16 v[80:83], v[168:171], v[204:207], v[80:83]
	v_mfma_f32_16x16x32_bf16 v[68:71], v[160:163], v[212:215], v[68:71]
	v_mfma_f32_16x16x32_bf16 v[64:67], v[168:171], v[212:215], v[64:67]
	v_mfma_f32_16x16x32_bf16 v[132:135], v[164:167], v[188:191], v[132:135]
	v_mfma_f32_16x16x32_bf16 v[128:131], v[180:183], v[188:191], v[128:131]
	v_mfma_f32_16x16x32_bf16 v[116:119], v[164:167], v[200:203], v[116:119]
	v_mfma_f32_16x16x32_bf16 v[112:115], v[180:183], v[200:203], v[112:115]
	v_mfma_f32_16x16x32_bf16 v[84:87], v[164:167], v[208:211], v[84:87]
	v_mfma_f32_16x16x32_bf16 v[80:83], v[180:183], v[208:211], v[80:83]
	v_mfma_f32_16x16x32_bf16 v[68:71], v[164:167], v[216:219], v[68:71]
	v_mfma_f32_16x16x32_bf16 v[64:67], v[180:183], v[216:219], v[64:67]
	s_barrier
	s_add_i32 s77, s67, s55
	v_lshl_add_u64 v[196:197], s[50:51], 0, v[146:147]
	s_mov_b32 m0, s77
	ds_read_b128 v[184:187], v177 offset:16384
	ds_read_b128 v[188:191], v177 offset:17408
	ds_read_b128 v[192:195], v177 offset:18432
	ds_read_b128 v[200:203], v177 offset:19456
	ds_read_b128 v[204:207], v177 offset:20480
	ds_read_b128 v[208:211], v177 offset:21504
	ds_read_b128 v[212:215], v177 offset:22528
	ds_read_b128 v[216:219], v177 offset:23552
	global_load_lds_dwordx4 v[196:197], off
	s_add_i32 m0, s77, 0x2000
	s_add_u32 s78, s50, 0x40000
	v_lshl_add_u64 v[220:221], s[50:51], 0, v[150:151]
	s_addc_u32 s79, s51, 0
	s_add_i32 s77, s70, s55
	global_load_lds_dwordx4 v[220:221], off
	v_lshl_add_u64 v[222:223], s[78:79], 0, v[146:147]
	s_mov_b32 m0, s77
	v_lshl_add_u64 v[224:225], s[52:53], 0, v[148:149]
	global_load_lds_dwordx4 v[222:223], off
	v_lshl_add_u64 v[222:223], s[78:79], 0, v[150:151]
	s_add_i32 m0, s77, 0x2000
	s_nop 0
	global_load_lds_dwordx4 v[222:223], off
	v_lshl_add_u64 v[222:223], s[52:53], 0, v[144:145]
	s_mov_b32 m0, s47
	s_nop 0
	global_load_lds_dwordx4 v[222:223], off
	s_mov_b32 m0, s56
	s_nop 0
	global_load_lds_dwordx4 v[224:225], off
	s_waitcnt vmcnt(8)
	s_waitcnt lgkmcnt(0)
	s_barrier
	s_waitcnt lgkmcnt(0)
	v_mfma_f32_16x16x32_bf16 v[60:63], v[88:91], v[184:187], v[60:63]
	v_mfma_f32_16x16x32_bf16 v[56:59], v[96:99], v[184:187], v[56:59]
	v_mfma_f32_16x16x32_bf16 v[44:47], v[88:91], v[192:195], v[44:47]
	v_mfma_f32_16x16x32_bf16 v[40:43], v[96:99], v[192:195], v[40:43]
	v_mfma_f32_16x16x32_bf16 v[28:31], v[88:91], v[204:207], v[28:31]
	v_mfma_f32_16x16x32_bf16 v[24:27], v[96:99], v[204:207], v[24:27]
	v_mfma_f32_16x16x32_bf16 v[12:15], v[88:91], v[212:215], v[12:15]
	v_mfma_f32_16x16x32_bf16 v[8:11], v[96:99], v[212:215], v[8:11]
	v_mfma_f32_16x16x32_bf16 v[60:63], v[92:95], v[188:191], v[60:63]
	v_mfma_f32_16x16x32_bf16 v[56:59], v[100:103], v[188:191], v[56:59]
	v_mfma_f32_16x16x32_bf16 v[44:47], v[92:95], v[200:203], v[44:47]
	v_mfma_f32_16x16x32_bf16 v[40:43], v[100:103], v[200:203], v[40:43]
	v_mfma_f32_16x16x32_bf16 v[28:31], v[92:95], v[208:211], v[28:31]
	v_mfma_f32_16x16x32_bf16 v[24:27], v[100:103], v[208:211], v[24:27]
	v_mfma_f32_16x16x32_bf16 v[12:15], v[92:95], v[216:219], v[12:15]
	v_mfma_f32_16x16x32_bf16 v[8:11], v[100:103], v[216:219], v[8:11]
	v_mfma_f32_16x16x32_bf16 v[52:55], v[160:163], v[184:187], v[52:55]
	v_mfma_f32_16x16x32_bf16 v[48:51], v[168:171], v[184:187], v[48:51]
	v_mfma_f32_16x16x32_bf16 v[36:39], v[160:163], v[192:195], v[36:39]
	v_mfma_f32_16x16x32_bf16 v[32:35], v[168:171], v[192:195], v[32:35]
	v_mfma_f32_16x16x32_bf16 v[20:23], v[160:163], v[204:207], v[20:23]
	v_mfma_f32_16x16x32_bf16 v[16:19], v[168:171], v[204:207], v[16:19]
	v_mfma_f32_16x16x32_bf16 v[4:7], v[160:163], v[212:215], v[4:7]
	v_mfma_f32_16x16x32_bf16 v[0:3], v[168:171], v[212:215], v[0:3]
	v_mfma_f32_16x16x32_bf16 v[52:55], v[164:167], v[188:191], v[52:55]
	v_mfma_f32_16x16x32_bf16 v[48:51], v[180:183], v[188:191], v[48:51]
	v_mfma_f32_16x16x32_bf16 v[36:39], v[164:167], v[200:203], v[36:39]
	v_mfma_f32_16x16x32_bf16 v[32:35], v[180:183], v[200:203], v[32:35]
	v_mfma_f32_16x16x32_bf16 v[20:23], v[164:167], v[208:211], v[20:23]
	v_mfma_f32_16x16x32_bf16 v[16:19], v[180:183], v[208:211], v[16:19]
	v_mfma_f32_16x16x32_bf16 v[4:7], v[164:167], v[216:219], v[4:7]
	v_mfma_f32_16x16x32_bf16 v[0:3], v[180:183], v[216:219], v[0:3]
	s_barrier
	s_add_i32 s77, 0, 0x18000
	s_add_i32 s78, 0, 0x1c000
	v_add_u32_e32 v100, s77, v173
	v_add_u32_e32 v179, s78, v173
	ds_read_b128 v[88:91], v100
	ds_read_b128 v[92:95], v100 offset:1024
	ds_read_b128 v[96:99], v100 offset:2048
	ds_read_b128 v[100:103], v100 offset:3072
	ds_read_b128 v[160:163], v179
	ds_read_b128 v[164:167], v179 offset:1024
	ds_read_b128 v[168:171], v179 offset:2048
	ds_read_b128 v[180:183], v179 offset:3072
	s_add_u32 s52, s52, 0x40000
	s_addc_u32 s53, s53, 0
	s_mov_b32 m0, s57
	v_lshl_add_u64 v[226:227], s[52:53], 0, v[144:145]
	ds_read_b128 v[184:187], v177 offset:32768
	ds_read_b128 v[188:191], v177 offset:33792
	ds_read_b128 v[192:195], v177 offset:34816
	ds_read_b128 v[200:203], v177 offset:35840
	ds_read_b128 v[204:207], v177 offset:36864
	ds_read_b128 v[208:211], v177 offset:37888
	ds_read_b128 v[212:215], v177 offset:38912
	ds_read_b128 v[216:219], v177 offset:39936
	global_load_lds_dwordx4 v[226:227], off
	v_lshl_add_u64 v[226:227], s[52:53], 0, v[148:149]
	s_mov_b32 m0, s58
	s_nop 0
	global_load_lds_dwordx4 v[226:227], off
	s_waitcnt vmcnt(8)
	s_waitcnt lgkmcnt(0)
	s_barrier
	s_waitcnt lgkmcnt(0)
	v_mfma_f32_16x16x32_bf16 v[140:143], v[88:91], v[184:187], v[140:143]
	v_mfma_f32_16x16x32_bf16 v[136:139], v[96:99], v[184:187], v[136:139]
	v_mfma_f32_16x16x32_bf16 v[124:127], v[88:91], v[192:195], v[124:127]
	v_mfma_f32_16x16x32_bf16 v[120:123], v[96:99], v[192:195], v[120:123]
	v_mfma_f32_16x16x32_bf16 v[108:111], v[88:91], v[204:207], v[108:111]
	v_mfma_f32_16x16x32_bf16 v[104:107], v[96:99], v[204:207], v[104:107]
	v_mfma_f32_16x16x32_bf16 v[76:79], v[88:91], v[212:215], v[76:79]
	v_mfma_f32_16x16x32_bf16 v[72:75], v[96:99], v[212:215], v[72:75]
	v_mfma_f32_16x16x32_bf16 v[140:143], v[92:95], v[188:191], v[140:143]
	v_mfma_f32_16x16x32_bf16 v[136:139], v[100:103], v[188:191], v[136:139]
	v_mfma_f32_16x16x32_bf16 v[124:127], v[92:95], v[200:203], v[124:127]
	v_mfma_f32_16x16x32_bf16 v[120:123], v[100:103], v[200:203], v[120:123]
	v_mfma_f32_16x16x32_bf16 v[108:111], v[92:95], v[208:211], v[108:111]
	v_mfma_f32_16x16x32_bf16 v[104:107], v[100:103], v[208:211], v[104:107]
	v_mfma_f32_16x16x32_bf16 v[76:79], v[92:95], v[216:219], v[76:79]
	v_mfma_f32_16x16x32_bf16 v[72:75], v[100:103], v[216:219], v[72:75]
	v_mfma_f32_16x16x32_bf16 v[132:135], v[160:163], v[184:187], v[132:135]
	v_mfma_f32_16x16x32_bf16 v[128:131], v[168:171], v[184:187], v[128:131]
	v_mfma_f32_16x16x32_bf16 v[116:119], v[160:163], v[192:195], v[116:119]
	v_mfma_f32_16x16x32_bf16 v[112:115], v[168:171], v[192:195], v[112:115]
	v_mfma_f32_16x16x32_bf16 v[84:87], v[160:163], v[204:207], v[84:87]
	v_mfma_f32_16x16x32_bf16 v[80:83], v[168:171], v[204:207], v[80:83]
	v_mfma_f32_16x16x32_bf16 v[68:71], v[160:163], v[212:215], v[68:71]
	v_mfma_f32_16x16x32_bf16 v[64:67], v[168:171], v[212:215], v[64:67]
	v_mfma_f32_16x16x32_bf16 v[132:135], v[164:167], v[188:191], v[132:135]
	v_mfma_f32_16x16x32_bf16 v[128:131], v[180:183], v[188:191], v[128:131]
	v_mfma_f32_16x16x32_bf16 v[116:119], v[164:167], v[200:203], v[116:119]
	v_mfma_f32_16x16x32_bf16 v[112:115], v[180:183], v[200:203], v[112:115]
	v_mfma_f32_16x16x32_bf16 v[84:87], v[164:167], v[208:211], v[84:87]
	v_mfma_f32_16x16x32_bf16 v[80:83], v[180:183], v[208:211], v[80:83]
	v_mfma_f32_16x16x32_bf16 v[68:71], v[164:167], v[216:219], v[68:71]
	v_mfma_f32_16x16x32_bf16 v[64:67], v[180:183], v[216:219], v[64:67]
	s_barrier
	s_add_i32 s52, s77, s55
	v_lshl_add_u64 v[196:197], v[196:197], 0, s[8:9]
	s_mov_b32 m0, s52
	ds_read_b128 v[184:187], v177 offset:49152
	ds_read_b128 v[188:191], v177 offset:50176
	ds_read_b128 v[192:195], v177 offset:51200
	ds_read_b128 v[200:203], v177 offset:52224
	ds_read_b128 v[204:207], v177 offset:53248
	ds_read_b128 v[208:211], v177 offset:54272
	ds_read_b128 v[212:215], v177 offset:55296
	ds_read_b128 v[216:219], v177 offset:56320
	global_load_lds_dwordx4 v[196:197], off
	s_add_i32 m0, s52, 0x2000
	s_add_u32 s50, s50, 0x40080
	v_lshl_add_u64 v[196:197], v[220:221], 0, s[8:9]
	s_addc_u32 s51, s51, 0
	s_add_i32 s52, s78, s55
	global_load_lds_dwordx4 v[196:197], off
	v_lshl_add_u64 v[196:197], s[50:51], 0, v[146:147]
	s_mov_b32 m0, s52
	s_nop 0
	global_load_lds_dwordx4 v[196:197], off
	v_lshl_add_u64 v[196:197], s[50:51], 0, v[150:151]
	s_add_i32 m0, s52, 0x2000
	s_nop 0
	global_load_lds_dwordx4 v[196:197], off
	v_lshl_add_u64 v[196:197], v[222:223], 0, s[8:9]
	s_mov_b32 m0, s61
	s_nop 0
	global_load_lds_dwordx4 v[196:197], off
	v_lshl_add_u64 v[196:197], v[224:225], 0, s[8:9]
	s_mov_b32 m0, s62
	s_nop 0
	global_load_lds_dwordx4 v[196:197], off
	s_waitcnt vmcnt(8)
	s_waitcnt lgkmcnt(0)
	s_barrier
	s_waitcnt lgkmcnt(0)
	v_mfma_f32_16x16x32_bf16 v[60:63], v[88:91], v[184:187], v[60:63]
	v_mfma_f32_16x16x32_bf16 v[56:59], v[96:99], v[184:187], v[56:59]
	v_mfma_f32_16x16x32_bf16 v[44:47], v[88:91], v[192:195], v[44:47]
	v_mfma_f32_16x16x32_bf16 v[40:43], v[96:99], v[192:195], v[40:43]
	v_mfma_f32_16x16x32_bf16 v[28:31], v[88:91], v[204:207], v[28:31]
	v_mfma_f32_16x16x32_bf16 v[24:27], v[96:99], v[204:207], v[24:27]
	v_mfma_f32_16x16x32_bf16 v[12:15], v[88:91], v[212:215], v[12:15]
	v_mfma_f32_16x16x32_bf16 v[8:11], v[96:99], v[212:215], v[8:11]
	v_mfma_f32_16x16x32_bf16 v[60:63], v[92:95], v[188:191], v[60:63]
	v_mfma_f32_16x16x32_bf16 v[56:59], v[100:103], v[188:191], v[56:59]
	v_mfma_f32_16x16x32_bf16 v[44:47], v[92:95], v[200:203], v[44:47]
	v_mfma_f32_16x16x32_bf16 v[40:43], v[100:103], v[200:203], v[40:43]
	v_mfma_f32_16x16x32_bf16 v[28:31], v[92:95], v[208:211], v[28:31]
	v_mfma_f32_16x16x32_bf16 v[24:27], v[100:103], v[208:211], v[24:27]
	v_mfma_f32_16x16x32_bf16 v[12:15], v[92:95], v[216:219], v[12:15]
	v_mfma_f32_16x16x32_bf16 v[8:11], v[100:103], v[216:219], v[8:11]
	v_mfma_f32_16x16x32_bf16 v[52:55], v[160:163], v[184:187], v[52:55]
	v_mfma_f32_16x16x32_bf16 v[48:51], v[168:171], v[184:187], v[48:51]
	v_mfma_f32_16x16x32_bf16 v[36:39], v[160:163], v[192:195], v[36:39]
	v_mfma_f32_16x16x32_bf16 v[32:35], v[168:171], v[192:195], v[32:35]
	v_mfma_f32_16x16x32_bf16 v[20:23], v[160:163], v[204:207], v[20:23]
	v_mfma_f32_16x16x32_bf16 v[16:19], v[168:171], v[204:207], v[16:19]
	v_mfma_f32_16x16x32_bf16 v[4:7], v[160:163], v[212:215], v[4:7]
	v_mfma_f32_16x16x32_bf16 v[0:3], v[168:171], v[212:215], v[0:3]
	v_mfma_f32_16x16x32_bf16 v[52:55], v[164:167], v[188:191], v[52:55]
	v_mfma_f32_16x16x32_bf16 v[48:51], v[180:183], v[188:191], v[48:51]
	v_mfma_f32_16x16x32_bf16 v[36:39], v[164:167], v[200:203], v[36:39]
	v_mfma_f32_16x16x32_bf16 v[32:35], v[180:183], v[200:203], v[32:35]
	v_mfma_f32_16x16x32_bf16 v[20:23], v[164:167], v[208:211], v[20:23]
	v_mfma_f32_16x16x32_bf16 v[16:19], v[180:183], v[208:211], v[16:19]
	v_mfma_f32_16x16x32_bf16 v[4:7], v[164:167], v[216:219], v[4:7]
	v_mfma_f32_16x16x32_bf16 v[0:3], v[180:183], v[216:219], v[0:3]
	s_barrier
	s_add_i32 s76, s76, 2
	s_add_u32 s48, s48, 0x100
	s_addc_u32 s49, s49, 0
	s_add_u32 s45, s45, 0x100
	s_addc_u32 s75, s75, 0
	s_cmp_gt_u32 s76, 13
	s_cbranch_scc0 .LBB0_1576
	s_and_b64 vcc, exec, s[12:13]
	s_cbranch_vccz .LBB0_1579
	s_barrier

.LBB0_1671:
	ds_read_b128 v[64:67], v176
	ds_read_b128 v[68:71], v176 offset:1024
	ds_read_b128 v[76:79], v176 offset:2048
	ds_read_b128 v[80:83], v176 offset:3072
	ds_read_b128 v[184:187], v177
	ds_read_b128 v[188:191], v177 offset:1024
	ds_read_b128 v[192:195], v177 offset:2048
	ds_read_b128 v[200:203], v177 offset:3072
	s_add_u32 s26, s24, 0xfffc0080
	s_addc_u32 s27, s25, -1
	s_cmp_eq_u32 s66, 12
	s_cselect_b32 s43, s1, s27
	s_cselect_b32 s42, s10, s26
	s_cselect_b32 s27, s11, s65
	s_cselect_b32 s26, s17, s19
	v_lshl_add_u64 v[162:163], s[24:25], 0, v[154:155]
	s_add_i32 m0, s49, 0xc000
	ds_read_b128 v[204:207], v178
	ds_read_b128 v[208:211], v178 offset:1024
	ds_read_b128 v[212:215], v178 offset:2048
	ds_read_b128 v[216:219], v178 offset:3072
	ds_read_b128 v[220:223], v178 offset:4096
	ds_read_b128 v[224:227], v178 offset:5120
	ds_read_b128 v[228:231], v178 offset:6144
	ds_read_b128 v[232:235], v178 offset:7168
	global_load_lds_dwordx4 v[162:163], off
	v_lshl_add_u64 v[162:163], s[24:25], 0, v[156:157]
	s_add_i32 m0, s49, 0xe000
	s_nop 0
	global_load_lds_dwordx4 v[162:163], off
	s_waitcnt vmcnt(8)
	s_waitcnt lgkmcnt(0)
	s_barrier
	s_waitcnt lgkmcnt(0)
	v_mfma_f32_16x16x32_bf16 v[140:143], v[64:67], v[204:207], v[140:143]
	v_mfma_f32_16x16x32_bf16 v[132:135], v[76:79], v[204:207], v[132:135]
	v_mfma_f32_16x16x32_bf16 v[124:127], v[64:67], v[212:215], v[124:127]
	v_mfma_f32_16x16x32_bf16 v[120:123], v[76:79], v[212:215], v[120:123]
	v_mfma_f32_16x16x32_bf16 v[108:111], v[64:67], v[220:223], v[108:111]
	v_mfma_f32_16x16x32_bf16 v[104:107], v[76:79], v[220:223], v[104:107]
	v_mfma_f32_16x16x32_bf16 v[92:95], v[64:67], v[228:231], v[92:95]
	v_mfma_f32_16x16x32_bf16 v[88:91], v[76:79], v[228:231], v[88:91]
	v_mfma_f32_16x16x32_bf16 v[140:143], v[68:71], v[208:211], v[140:143]
	v_mfma_f32_16x16x32_bf16 v[132:135], v[80:83], v[208:211], v[132:135]
	v_mfma_f32_16x16x32_bf16 v[124:127], v[68:71], v[216:219], v[124:127]
	v_mfma_f32_16x16x32_bf16 v[120:123], v[80:83], v[216:219], v[120:123]
	v_mfma_f32_16x16x32_bf16 v[108:111], v[68:71], v[224:227], v[108:111]
	v_mfma_f32_16x16x32_bf16 v[104:107], v[80:83], v[224:227], v[104:107]
	v_mfma_f32_16x16x32_bf16 v[92:95], v[68:71], v[232:235], v[92:95]
	v_mfma_f32_16x16x32_bf16 v[88:91], v[80:83], v[232:235], v[88:91]
	v_mfma_f32_16x16x32_bf16 v[136:139], v[184:187], v[204:207], v[136:139]
	v_mfma_f32_16x16x32_bf16 v[128:131], v[192:195], v[204:207], v[128:131]
	v_mfma_f32_16x16x32_bf16 v[116:119], v[184:187], v[212:215], v[116:119]
	v_mfma_f32_16x16x32_bf16 v[112:115], v[192:195], v[212:215], v[112:115]
	v_mfma_f32_16x16x32_bf16 v[100:103], v[184:187], v[220:223], v[100:103]
	v_mfma_f32_16x16x32_bf16 v[96:99], v[192:195], v[220:223], v[96:99]
	v_mfma_f32_16x16x32_bf16 v[84:87], v[184:187], v[228:231], v[84:87]
	v_mfma_f32_16x16x32_bf16 v[72:75], v[192:195], v[228:231], v[72:75]
	v_mfma_f32_16x16x32_bf16 v[136:139], v[188:191], v[208:211], v[136:139]
	v_mfma_f32_16x16x32_bf16 v[128:131], v[200:203], v[208:211], v[128:131]
	v_mfma_f32_16x16x32_bf16 v[116:119], v[188:191], v[216:219], v[116:119]
	v_mfma_f32_16x16x32_bf16 v[112:115], v[200:203], v[216:219], v[112:115]
	v_mfma_f32_16x16x32_bf16 v[100:103], v[188:191], v[224:227], v[100:103]
	v_mfma_f32_16x16x32_bf16 v[96:99], v[200:203], v[224:227], v[96:99]
	v_mfma_f32_16x16x32_bf16 v[84:87], v[188:191], v[232:235], v[84:87]
	v_mfma_f32_16x16x32_bf16 v[72:75], v[200:203], v[232:235], v[72:75]
	s_barrier
	s_add_i32 s67, s58, s48
	v_lshl_add_u64 v[162:163], s[26:27], 0, v[146:147]
	s_mov_b32 m0, s67
	ds_read_b128 v[204:207], v178 offset:16384
	ds_read_b128 v[208:211], v178 offset:17408
	ds_read_b128 v[212:215], v178 offset:18432
	ds_read_b128 v[216:219], v178 offset:19456
	ds_read_b128 v[220:223], v178 offset:20480
	ds_read_b128 v[224:227], v178 offset:21504
	ds_read_b128 v[228:231], v178 offset:22528
	ds_read_b128 v[232:235], v178 offset:23552
	global_load_lds_dwordx4 v[162:163], off
	s_add_i32 m0, s67, 0x2000
	s_add_u32 s70, s26, 0x40000
	v_lshl_add_u64 v[196:197], s[26:27], 0, v[150:151]
	s_addc_u32 s71, s27, 0
	s_add_i32 s67, s59, s48
	global_load_lds_dwordx4 v[196:197], off
	v_lshl_add_u64 v[236:237], s[70:71], 0, v[146:147]
	s_mov_b32 m0, s67
	v_lshl_add_u64 v[238:239], s[42:43], 0, v[148:149]
	global_load_lds_dwordx4 v[236:237], off
	v_lshl_add_u64 v[236:237], s[70:71], 0, v[150:151]
	s_add_i32 m0, s67, 0x2000
	s_nop 0
	global_load_lds_dwordx4 v[236:237], off
	v_lshl_add_u64 v[236:237], s[42:43], 0, v[144:145]
	s_mov_b32 m0, s49
	s_nop 0
	global_load_lds_dwordx4 v[236:237], off
	s_mov_b32 m0, s50
	s_nop 0
	global_load_lds_dwordx4 v[238:239], off
	s_waitcnt vmcnt(8)
	s_waitcnt lgkmcnt(0)
	s_barrier
	s_waitcnt lgkmcnt(0)
	v_mfma_f32_16x16x32_bf16 v[60:63], v[64:67], v[204:207], v[60:63]
	v_mfma_f32_16x16x32_bf16 v[56:59], v[76:79], v[204:207], v[56:59]
	v_mfma_f32_16x16x32_bf16 v[44:47], v[64:67], v[212:215], v[44:47]
	v_mfma_f32_16x16x32_bf16 v[40:43], v[76:79], v[212:215], v[40:43]
	v_mfma_f32_16x16x32_bf16 v[28:31], v[64:67], v[220:223], v[28:31]
	v_mfma_f32_16x16x32_bf16 v[24:27], v[76:79], v[220:223], v[24:27]
	v_mfma_f32_16x16x32_bf16 v[12:15], v[64:67], v[228:231], v[12:15]
	v_mfma_f32_16x16x32_bf16 v[8:11], v[76:79], v[228:231], v[8:11]
	v_mfma_f32_16x16x32_bf16 v[60:63], v[68:71], v[208:211], v[60:63]
	v_mfma_f32_16x16x32_bf16 v[56:59], v[80:83], v[208:211], v[56:59]
	v_mfma_f32_16x16x32_bf16 v[44:47], v[68:71], v[216:219], v[44:47]
	v_mfma_f32_16x16x32_bf16 v[40:43], v[80:83], v[216:219], v[40:43]
	v_mfma_f32_16x16x32_bf16 v[28:31], v[68:71], v[224:227], v[28:31]
	v_mfma_f32_16x16x32_bf16 v[24:27], v[80:83], v[224:227], v[24:27]
	v_mfma_f32_16x16x32_bf16 v[12:15], v[68:71], v[232:235], v[12:15]
	v_mfma_f32_16x16x32_bf16 v[8:11], v[80:83], v[232:235], v[8:11]
	v_mfma_f32_16x16x32_bf16 v[52:55], v[184:187], v[204:207], v[52:55]
	v_mfma_f32_16x16x32_bf16 v[48:51], v[192:195], v[204:207], v[48:51]
	v_mfma_f32_16x16x32_bf16 v[36:39], v[184:187], v[212:215], v[36:39]
	v_mfma_f32_16x16x32_bf16 v[32:35], v[192:195], v[212:215], v[32:35]
	v_mfma_f32_16x16x32_bf16 v[20:23], v[184:187], v[220:223], v[20:23]
	v_mfma_f32_16x16x32_bf16 v[16:19], v[192:195], v[220:223], v[16:19]
	v_mfma_f32_16x16x32_bf16 v[4:7], v[184:187], v[228:231], v[4:7]
	v_mfma_f32_16x16x32_bf16 v[0:3], v[192:195], v[228:231], v[0:3]
	v_mfma_f32_16x16x32_bf16 v[52:55], v[188:191], v[208:211], v[52:55]
	v_mfma_f32_16x16x32_bf16 v[48:51], v[200:203], v[208:211], v[48:51]
	v_mfma_f32_16x16x32_bf16 v[36:39], v[188:191], v[216:219], v[36:39]
	v_mfma_f32_16x16x32_bf16 v[32:35], v[200:203], v[216:219], v[32:35]
	v_mfma_f32_16x16x32_bf16 v[20:23], v[188:191], v[224:227], v[20:23]
	v_mfma_f32_16x16x32_bf16 v[16:19], v[200:203], v[224:227], v[16:19]
	v_mfma_f32_16x16x32_bf16 v[4:7], v[188:191], v[232:235], v[4:7]
	v_mfma_f32_16x16x32_bf16 v[0:3], v[200:203], v[232:235], v[0:3]
	s_barrier
	s_add_i32 s67, 0, 0x18000
	s_add_i32 s70, 0, 0x1c000
	v_add_u32_e32 v80, s67, v166
	v_add_u32_e32 v164, s70, v166
	ds_read_b128 v[64:67], v80
	ds_read_b128 v[68:71], v80 offset:1024
	ds_read_b128 v[76:79], v80 offset:2048
	ds_read_b128 v[80:83], v80 offset:3072
	ds_read_b128 v[184:187], v164
	ds_read_b128 v[188:191], v164 offset:1024
	ds_read_b128 v[192:195], v164 offset:2048
	ds_read_b128 v[200:203], v164 offset:3072
	s_add_u32 s42, s42, 0x40000
	s_addc_u32 s43, s43, 0
	s_mov_b32 m0, s51
	v_lshl_add_u64 v[240:241], s[42:43], 0, v[144:145]
	ds_read_b128 v[204:207], v178 offset:32768
	ds_read_b128 v[208:211], v178 offset:33792
	ds_read_b128 v[212:215], v178 offset:34816
	ds_read_b128 v[216:219], v178 offset:35840
	ds_read_b128 v[220:223], v178 offset:36864
	ds_read_b128 v[224:227], v178 offset:37888
	ds_read_b128 v[228:231], v178 offset:38912
	ds_read_b128 v[232:235], v178 offset:39936
	global_load_lds_dwordx4 v[240:241], off
	v_lshl_add_u64 v[240:241], s[42:43], 0, v[148:149]
	s_mov_b32 m0, s52
	s_nop 0
	global_load_lds_dwordx4 v[240:241], off
	s_waitcnt vmcnt(8)
	s_waitcnt lgkmcnt(0)
	s_barrier
	s_waitcnt lgkmcnt(0)
	v_mfma_f32_16x16x32_bf16 v[140:143], v[64:67], v[204:207], v[140:143]
	v_mfma_f32_16x16x32_bf16 v[132:135], v[76:79], v[204:207], v[132:135]
	v_mfma_f32_16x16x32_bf16 v[124:127], v[64:67], v[212:215], v[124:127]
	v_mfma_f32_16x16x32_bf16 v[120:123], v[76:79], v[212:215], v[120:123]
	v_mfma_f32_16x16x32_bf16 v[108:111], v[64:67], v[220:223], v[108:111]
	v_mfma_f32_16x16x32_bf16 v[104:107], v[76:79], v[220:223], v[104:107]
	v_mfma_f32_16x16x32_bf16 v[92:95], v[64:67], v[228:231], v[92:95]
	v_mfma_f32_16x16x32_bf16 v[88:91], v[76:79], v[228:231], v[88:91]
	v_mfma_f32_16x16x32_bf16 v[140:143], v[68:71], v[208:211], v[140:143]
	v_mfma_f32_16x16x32_bf16 v[132:135], v[80:83], v[208:211], v[132:135]
	v_mfma_f32_16x16x32_bf16 v[124:127], v[68:71], v[216:219], v[124:127]
	v_mfma_f32_16x16x32_bf16 v[120:123], v[80:83], v[216:219], v[120:123]
	v_mfma_f32_16x16x32_bf16 v[108:111], v[68:71], v[224:227], v[108:111]
	v_mfma_f32_16x16x32_bf16 v[104:107], v[80:83], v[224:227], v[104:107]
	v_mfma_f32_16x16x32_bf16 v[92:95], v[68:71], v[232:235], v[92:95]
	v_mfma_f32_16x16x32_bf16 v[88:91], v[80:83], v[232:235], v[88:91]
	v_mfma_f32_16x16x32_bf16 v[136:139], v[184:187], v[204:207], v[136:139]
	v_mfma_f32_16x16x32_bf16 v[128:131], v[192:195], v[204:207], v[128:131]
	v_mfma_f32_16x16x32_bf16 v[116:119], v[184:187], v[212:215], v[116:119]
	v_mfma_f32_16x16x32_bf16 v[112:115], v[192:195], v[212:215], v[112:115]
	v_mfma_f32_16x16x32_bf16 v[100:103], v[184:187], v[220:223], v[100:103]
	v_mfma_f32_16x16x32_bf16 v[96:99], v[192:195], v[220:223], v[96:99]
	v_mfma_f32_16x16x32_bf16 v[84:87], v[184:187], v[228:231], v[84:87]
	v_mfma_f32_16x16x32_bf16 v[72:75], v[192:195], v[228:231], v[72:75]
	v_mfma_f32_16x16x32_bf16 v[136:139], v[188:191], v[208:211], v[136:139]
	v_mfma_f32_16x16x32_bf16 v[128:131], v[200:203], v[208:211], v[128:131]
	v_mfma_f32_16x16x32_bf16 v[116:119], v[188:191], v[216:219], v[116:119]
	v_mfma_f32_16x16x32_bf16 v[112:115], v[200:203], v[216:219], v[112:115]
	v_mfma_f32_16x16x32_bf16 v[100:103], v[188:191], v[224:227], v[100:103]
	v_mfma_f32_16x16x32_bf16 v[96:99], v[200:203], v[224:227], v[96:99]
	v_mfma_f32_16x16x32_bf16 v[84:87], v[188:191], v[232:235], v[84:87]
	v_mfma_f32_16x16x32_bf16 v[72:75], v[200:203], v[232:235], v[72:75]
	s_barrier
	s_add_i32 s42, s67, s48
	v_lshl_add_u64 v[162:163], v[162:163], 0, s[12:13]
	s_mov_b32 m0, s42
	ds_read_b128 v[204:207], v178 offset:49152
	ds_read_b128 v[208:211], v178 offset:50176
	ds_read_b128 v[212:215], v178 offset:51200
	ds_read_b128 v[216:219], v178 offset:52224
	ds_read_b128 v[220:223], v178 offset:53248
	ds_read_b128 v[224:227], v178 offset:54272
	ds_read_b128 v[228:231], v178 offset:55296
	ds_read_b128 v[232:235], v178 offset:56320
	global_load_lds_dwordx4 v[162:163], off
	s_add_i32 m0, s42, 0x2000
	s_add_u32 s26, s26, 0x40080
	v_lshl_add_u64 v[162:163], v[196:197], 0, s[12:13]
	s_addc_u32 s27, s27, 0
	s_add_i32 s42, s70, s48
	global_load_lds_dwordx4 v[162:163], off
	v_lshl_add_u64 v[162:163], s[26:27], 0, v[146:147]
	s_mov_b32 m0, s42
	s_nop 0
	global_load_lds_dwordx4 v[162:163], off
	v_lshl_add_u64 v[162:163], s[26:27], 0, v[150:151]
	s_add_i32 m0, s42, 0x2000
	s_nop 0
	global_load_lds_dwordx4 v[162:163], off
	v_lshl_add_u64 v[162:163], v[236:237], 0, s[12:13]
	s_mov_b32 m0, s55
	s_nop 0
	global_load_lds_dwordx4 v[162:163], off
	v_lshl_add_u64 v[162:163], v[238:239], 0, s[12:13]
	s_mov_b32 m0, s56
	s_nop 0
	global_load_lds_dwordx4 v[162:163], off
	s_waitcnt vmcnt(8)
	s_waitcnt lgkmcnt(0)
	s_barrier
	s_waitcnt lgkmcnt(0)
	v_mfma_f32_16x16x32_bf16 v[60:63], v[64:67], v[204:207], v[60:63]
	v_mfma_f32_16x16x32_bf16 v[56:59], v[76:79], v[204:207], v[56:59]
	v_mfma_f32_16x16x32_bf16 v[44:47], v[64:67], v[212:215], v[44:47]
	v_mfma_f32_16x16x32_bf16 v[40:43], v[76:79], v[212:215], v[40:43]
	v_mfma_f32_16x16x32_bf16 v[28:31], v[64:67], v[220:223], v[28:31]
	v_mfma_f32_16x16x32_bf16 v[24:27], v[76:79], v[220:223], v[24:27]
	v_mfma_f32_16x16x32_bf16 v[12:15], v[64:67], v[228:231], v[12:15]
	v_mfma_f32_16x16x32_bf16 v[8:11], v[76:79], v[228:231], v[8:11]
	v_mfma_f32_16x16x32_bf16 v[60:63], v[68:71], v[208:211], v[60:63]
	v_mfma_f32_16x16x32_bf16 v[56:59], v[80:83], v[208:211], v[56:59]
	v_mfma_f32_16x16x32_bf16 v[44:47], v[68:71], v[216:219], v[44:47]
	v_mfma_f32_16x16x32_bf16 v[40:43], v[80:83], v[216:219], v[40:43]
	v_mfma_f32_16x16x32_bf16 v[28:31], v[68:71], v[224:227], v[28:31]
	v_mfma_f32_16x16x32_bf16 v[24:27], v[80:83], v[224:227], v[24:27]
	v_mfma_f32_16x16x32_bf16 v[12:15], v[68:71], v[232:235], v[12:15]
	v_mfma_f32_16x16x32_bf16 v[8:11], v[80:83], v[232:235], v[8:11]
	v_mfma_f32_16x16x32_bf16 v[52:55], v[184:187], v[204:207], v[52:55]
	v_mfma_f32_16x16x32_bf16 v[48:51], v[192:195], v[204:207], v[48:51]
	v_mfma_f32_16x16x32_bf16 v[36:39], v[184:187], v[212:215], v[36:39]
	v_mfma_f32_16x16x32_bf16 v[32:35], v[192:195], v[212:215], v[32:35]
	v_mfma_f32_16x16x32_bf16 v[20:23], v[184:187], v[220:223], v[20:23]
	v_mfma_f32_16x16x32_bf16 v[16:19], v[192:195], v[220:223], v[16:19]
	v_mfma_f32_16x16x32_bf16 v[4:7], v[184:187], v[228:231], v[4:7]
	v_mfma_f32_16x16x32_bf16 v[0:3], v[192:195], v[228:231], v[0:3]
	v_mfma_f32_16x16x32_bf16 v[52:55], v[188:191], v[208:211], v[52:55]
	v_mfma_f32_16x16x32_bf16 v[48:51], v[200:203], v[208:211], v[48:51]
	v_mfma_f32_16x16x32_bf16 v[36:39], v[188:191], v[216:219], v[36:39]
	v_mfma_f32_16x16x32_bf16 v[32:35], v[200:203], v[216:219], v[32:35]
	v_mfma_f32_16x16x32_bf16 v[20:23], v[188:191], v[224:227], v[20:23]
	v_mfma_f32_16x16x32_bf16 v[16:19], v[200:203], v[224:227], v[16:19]
	v_mfma_f32_16x16x32_bf16 v[4:7], v[188:191], v[232:235], v[4:7]
	v_mfma_f32_16x16x32_bf16 v[0:3], v[200:203], v[232:235], v[0:3]
	s_barrier
	s_add_i32 s66, s66, 2
	s_add_u32 s24, s24, 0x100
	s_addc_u32 s25, s25, 0
	s_add_u32 s19, s19, 0x100
	s_addc_u32 s65, s65, 0
	s_cmp_gt_u32 s66, 13
	s_cbranch_scc0 .LBB0_1671
	s_and_b64 vcc, exec, s[14:15]
	s_cbranch_vccz .LBB0_1674
	s_barrier

.LBB0_1786:
	ds_read_b128 v[144:147], v167
	ds_read_b128 v[148:151], v167 offset:1024
	ds_read_b128 v[152:155], v167 offset:2048
	ds_read_b128 v[156:159], v167 offset:3072
	ds_read_b128 v[160:163], v168
	ds_read_b128 v[170:173], v168 offset:1024
	ds_read_b128 v[174:177], v168 offset:2048
	ds_read_b128 v[178:181], v168 offset:3072
	s_add_u32 s16, s14, 0xfff50080
	s_addc_u32 s17, s15, -1
	s_cmp_eq_u32 s50, 40
	s_cselect_b32 s19, s3, s17
	s_cselect_b32 s18, s2, s16
	s_cselect_b32 s17, s13, s49
	s_cselect_b32 s16, s12, s48
	v_lshl_add_u64 v[214:215], s[14:15], 0, v[136:137]
	s_add_i32 m0, s24, 0xc000
	ds_read_b128 v[182:185], v169
	ds_read_b128 v[186:189], v169 offset:1024
	ds_read_b128 v[190:193], v169 offset:2048
	ds_read_b128 v[194:197], v169 offset:3072
	ds_read_b128 v[198:201], v169 offset:4096
	ds_read_b128 v[202:205], v169 offset:5120
	ds_read_b128 v[206:209], v169 offset:6144
	ds_read_b128 v[210:213], v169 offset:7168
	global_load_lds_dwordx4 v[214:215], off
	v_lshl_add_u64 v[214:215], s[14:15], 0, v[138:139]
	s_add_i32 m0, s24, 0xe000
	s_nop 0
	global_load_lds_dwordx4 v[214:215], off
	s_waitcnt vmcnt(8)
	s_waitcnt lgkmcnt(0)
	s_barrier
	s_waitcnt lgkmcnt(0)
	v_mfma_f32_16x16x32_bf16 v[124:127], v[144:147], v[182:185], v[124:127]
	v_mfma_f32_16x16x32_bf16 v[120:123], v[152:155], v[182:185], v[120:123]
	v_mfma_f32_16x16x32_bf16 v[108:111], v[144:147], v[190:193], v[108:111]
	v_mfma_f32_16x16x32_bf16 v[104:107], v[152:155], v[190:193], v[104:107]
	v_mfma_f32_16x16x32_bf16 v[92:95], v[144:147], v[198:201], v[92:95]
	v_mfma_f32_16x16x32_bf16 v[88:91], v[152:155], v[198:201], v[88:91]
	v_mfma_f32_16x16x32_bf16 v[76:79], v[144:147], v[206:209], v[76:79]
	v_mfma_f32_16x16x32_bf16 v[72:75], v[152:155], v[206:209], v[72:75]
	v_mfma_f32_16x16x32_bf16 v[124:127], v[148:151], v[186:189], v[124:127]
	v_mfma_f32_16x16x32_bf16 v[120:123], v[156:159], v[186:189], v[120:123]
	v_mfma_f32_16x16x32_bf16 v[108:111], v[148:151], v[194:197], v[108:111]
	v_mfma_f32_16x16x32_bf16 v[104:107], v[156:159], v[194:197], v[104:107]
	v_mfma_f32_16x16x32_bf16 v[92:95], v[148:151], v[202:205], v[92:95]
	v_mfma_f32_16x16x32_bf16 v[88:91], v[156:159], v[202:205], v[88:91]
	v_mfma_f32_16x16x32_bf16 v[76:79], v[148:151], v[210:213], v[76:79]
	v_mfma_f32_16x16x32_bf16 v[72:75], v[156:159], v[210:213], v[72:75]
	v_mfma_f32_16x16x32_bf16 v[116:119], v[160:163], v[182:185], v[116:119]
	v_mfma_f32_16x16x32_bf16 v[112:115], v[174:177], v[182:185], v[112:115]
	v_mfma_f32_16x16x32_bf16 v[100:103], v[160:163], v[190:193], v[100:103]
	v_mfma_f32_16x16x32_bf16 v[96:99], v[174:177], v[190:193], v[96:99]
	v_mfma_f32_16x16x32_bf16 v[84:87], v[160:163], v[198:201], v[84:87]
	v_mfma_f32_16x16x32_bf16 v[80:83], v[174:177], v[198:201], v[80:83]
	v_mfma_f32_16x16x32_bf16 v[68:71], v[160:163], v[206:209], v[68:71]
	v_mfma_f32_16x16x32_bf16 v[64:67], v[174:177], v[206:209], v[64:67]
	v_mfma_f32_16x16x32_bf16 v[116:119], v[170:173], v[186:189], v[116:119]
	v_mfma_f32_16x16x32_bf16 v[112:115], v[178:181], v[186:189], v[112:115]
	v_mfma_f32_16x16x32_bf16 v[100:103], v[170:173], v[194:197], v[100:103]
	v_mfma_f32_16x16x32_bf16 v[96:99], v[178:181], v[194:197], v[96:99]
	v_mfma_f32_16x16x32_bf16 v[84:87], v[170:173], v[202:205], v[84:87]
	v_mfma_f32_16x16x32_bf16 v[80:83], v[178:181], v[202:205], v[80:83]
	v_mfma_f32_16x16x32_bf16 v[68:71], v[170:173], v[210:213], v[68:71]
	v_mfma_f32_16x16x32_bf16 v[64:67], v[178:181], v[210:213], v[64:67]
	s_barrier
	s_add_i32 s51, s41, s23
	v_lshl_add_u64 v[214:215], s[16:17], 0, v[130:131]
	s_mov_b32 m0, s51
	ds_read_b128 v[182:185], v169 offset:16384
	ds_read_b128 v[186:189], v169 offset:17408
	ds_read_b128 v[190:193], v169 offset:18432
	ds_read_b128 v[194:197], v169 offset:19456
	ds_read_b128 v[198:201], v169 offset:20480
	ds_read_b128 v[202:205], v169 offset:21504
	ds_read_b128 v[206:209], v169 offset:22528
	ds_read_b128 v[210:213], v169 offset:23552
	global_load_lds_dwordx4 v[214:215], off
	s_add_i32 m0, s51, 0x2000
	s_add_u32 s52, s16, 0xb0000
	v_lshl_add_u64 v[216:217], s[16:17], 0, v[134:135]
	s_addc_u32 s53, s17, 0
	s_add_i32 s51, s42, s23
	global_load_lds_dwordx4 v[216:217], off
	v_lshl_add_u64 v[218:219], s[52:53], 0, v[130:131]
	s_mov_b32 m0, s51
	v_lshl_add_u64 v[220:221], s[18:19], 0, v[132:133]
	global_load_lds_dwordx4 v[218:219], off
	v_lshl_add_u64 v[218:219], s[52:53], 0, v[134:135]
	s_add_i32 m0, s51, 0x2000
	s_nop 0
	global_load_lds_dwordx4 v[218:219], off
	v_lshl_add_u64 v[218:219], s[18:19], 0, v[128:129]
	s_mov_b32 m0, s24
	s_nop 0
	global_load_lds_dwordx4 v[218:219], off
	s_mov_b32 m0, s25
	s_nop 0
	global_load_lds_dwordx4 v[220:221], off
	s_waitcnt vmcnt(8)
	s_waitcnt lgkmcnt(0)
	s_barrier
	s_waitcnt lgkmcnt(0)
	v_mfma_f32_16x16x32_bf16 v[60:63], v[144:147], v[182:185], v[60:63]
	v_mfma_f32_16x16x32_bf16 v[56:59], v[152:155], v[182:185], v[56:59]
	v_mfma_f32_16x16x32_bf16 v[44:47], v[144:147], v[190:193], v[44:47]
	v_mfma_f32_16x16x32_bf16 v[40:43], v[152:155], v[190:193], v[40:43]
	v_mfma_f32_16x16x32_bf16 v[28:31], v[144:147], v[198:201], v[28:31]
	v_mfma_f32_16x16x32_bf16 v[24:27], v[152:155], v[198:201], v[24:27]
	v_mfma_f32_16x16x32_bf16 v[12:15], v[144:147], v[206:209], v[12:15]
	v_mfma_f32_16x16x32_bf16 v[8:11], v[152:155], v[206:209], v[8:11]
	v_mfma_f32_16x16x32_bf16 v[60:63], v[148:151], v[186:189], v[60:63]
	v_mfma_f32_16x16x32_bf16 v[56:59], v[156:159], v[186:189], v[56:59]
	v_mfma_f32_16x16x32_bf16 v[44:47], v[148:151], v[194:197], v[44:47]
	v_mfma_f32_16x16x32_bf16 v[40:43], v[156:159], v[194:197], v[40:43]
	v_mfma_f32_16x16x32_bf16 v[28:31], v[148:151], v[202:205], v[28:31]
	v_mfma_f32_16x16x32_bf16 v[24:27], v[156:159], v[202:205], v[24:27]
	v_mfma_f32_16x16x32_bf16 v[12:15], v[148:151], v[210:213], v[12:15]
	v_mfma_f32_16x16x32_bf16 v[8:11], v[156:159], v[210:213], v[8:11]
	v_mfma_f32_16x16x32_bf16 v[52:55], v[160:163], v[182:185], v[52:55]
	v_mfma_f32_16x16x32_bf16 v[48:51], v[174:177], v[182:185], v[48:51]
	v_mfma_f32_16x16x32_bf16 v[36:39], v[160:163], v[190:193], v[36:39]
	v_mfma_f32_16x16x32_bf16 v[32:35], v[174:177], v[190:193], v[32:35]
	v_mfma_f32_16x16x32_bf16 v[20:23], v[160:163], v[198:201], v[20:23]
	v_mfma_f32_16x16x32_bf16 v[16:19], v[174:177], v[198:201], v[16:19]
	v_mfma_f32_16x16x32_bf16 v[4:7], v[160:163], v[206:209], v[4:7]
	v_mfma_f32_16x16x32_bf16 v[0:3], v[174:177], v[206:209], v[0:3]
	v_mfma_f32_16x16x32_bf16 v[52:55], v[170:173], v[186:189], v[52:55]
	v_mfma_f32_16x16x32_bf16 v[48:51], v[178:181], v[186:189], v[48:51]
	v_mfma_f32_16x16x32_bf16 v[36:39], v[170:173], v[194:197], v[36:39]
	v_mfma_f32_16x16x32_bf16 v[32:35], v[178:181], v[194:197], v[32:35]
	v_mfma_f32_16x16x32_bf16 v[20:23], v[170:173], v[202:205], v[20:23]
	v_mfma_f32_16x16x32_bf16 v[16:19], v[178:181], v[202:205], v[16:19]
	v_mfma_f32_16x16x32_bf16 v[4:7], v[170:173], v[210:213], v[4:7]
	v_mfma_f32_16x16x32_bf16 v[0:3], v[178:181], v[210:213], v[0:3]
	s_barrier
	s_add_i32 s51, 0, 0x18000
	s_add_i32 s52, 0, 0x1c000
	v_add_u32_e32 v156, s51, v165
	v_add_u32_e32 v178, s52, v165
	ds_read_b128 v[144:147], v156
	ds_read_b128 v[148:151], v156 offset:1024
	ds_read_b128 v[152:155], v156 offset:2048
	ds_read_b128 v[156:159], v156 offset:3072
	ds_read_b128 v[160:163], v178
	ds_read_b128 v[170:173], v178 offset:1024
	ds_read_b128 v[174:177], v178 offset:2048
	ds_read_b128 v[178:181], v178 offset:3072
	s_add_u32 s18, s18, 0xb0000
	s_addc_u32 s19, s19, 0
	s_mov_b32 m0, s26
	v_lshl_add_u64 v[222:223], s[18:19], 0, v[128:129]
	ds_read_b128 v[182:185], v169 offset:32768
	ds_read_b128 v[186:189], v169 offset:33792
	ds_read_b128 v[190:193], v169 offset:34816
	ds_read_b128 v[194:197], v169 offset:35840
	ds_read_b128 v[198:201], v169 offset:36864
	ds_read_b128 v[202:205], v169 offset:37888
	ds_read_b128 v[206:209], v169 offset:38912
	ds_read_b128 v[210:213], v169 offset:39936
	global_load_lds_dwordx4 v[222:223], off
	v_lshl_add_u64 v[222:223], s[18:19], 0, v[132:133]
	s_mov_b32 m0, s27
	s_nop 0
	global_load_lds_dwordx4 v[222:223], off
	s_waitcnt vmcnt(8)
	s_waitcnt lgkmcnt(0)
	s_barrier
	s_waitcnt lgkmcnt(0)
	v_mfma_f32_16x16x32_bf16 v[124:127], v[144:147], v[182:185], v[124:127]
	v_mfma_f32_16x16x32_bf16 v[120:123], v[152:155], v[182:185], v[120:123]
	v_mfma_f32_16x16x32_bf16 v[108:111], v[144:147], v[190:193], v[108:111]
	v_mfma_f32_16x16x32_bf16 v[104:107], v[152:155], v[190:193], v[104:107]
	v_mfma_f32_16x16x32_bf16 v[92:95], v[144:147], v[198:201], v[92:95]
	v_mfma_f32_16x16x32_bf16 v[88:91], v[152:155], v[198:201], v[88:91]
	v_mfma_f32_16x16x32_bf16 v[76:79], v[144:147], v[206:209], v[76:79]
	v_mfma_f32_16x16x32_bf16 v[72:75], v[152:155], v[206:209], v[72:75]
	v_mfma_f32_16x16x32_bf16 v[124:127], v[148:151], v[186:189], v[124:127]
	v_mfma_f32_16x16x32_bf16 v[120:123], v[156:159], v[186:189], v[120:123]
	v_mfma_f32_16x16x32_bf16 v[108:111], v[148:151], v[194:197], v[108:111]
	v_mfma_f32_16x16x32_bf16 v[104:107], v[156:159], v[194:197], v[104:107]
	v_mfma_f32_16x16x32_bf16 v[92:95], v[148:151], v[202:205], v[92:95]
	v_mfma_f32_16x16x32_bf16 v[88:91], v[156:159], v[202:205], v[88:91]
	v_mfma_f32_16x16x32_bf16 v[76:79], v[148:151], v[210:213], v[76:79]
	v_mfma_f32_16x16x32_bf16 v[72:75], v[156:159], v[210:213], v[72:75]
	v_mfma_f32_16x16x32_bf16 v[116:119], v[160:163], v[182:185], v[116:119]
	v_mfma_f32_16x16x32_bf16 v[112:115], v[174:177], v[182:185], v[112:115]
	v_mfma_f32_16x16x32_bf16 v[100:103], v[160:163], v[190:193], v[100:103]
	v_mfma_f32_16x16x32_bf16 v[96:99], v[174:177], v[190:193], v[96:99]
	v_mfma_f32_16x16x32_bf16 v[84:87], v[160:163], v[198:201], v[84:87]
	v_mfma_f32_16x16x32_bf16 v[80:83], v[174:177], v[198:201], v[80:83]
	v_mfma_f32_16x16x32_bf16 v[68:71], v[160:163], v[206:209], v[68:71]
	v_mfma_f32_16x16x32_bf16 v[64:67], v[174:177], v[206:209], v[64:67]
	v_mfma_f32_16x16x32_bf16 v[116:119], v[170:173], v[186:189], v[116:119]
	v_mfma_f32_16x16x32_bf16 v[112:115], v[178:181], v[186:189], v[112:115]
	v_mfma_f32_16x16x32_bf16 v[100:103], v[170:173], v[194:197], v[100:103]
	v_mfma_f32_16x16x32_bf16 v[96:99], v[178:181], v[194:197], v[96:99]
	v_mfma_f32_16x16x32_bf16 v[84:87], v[170:173], v[202:205], v[84:87]
	v_mfma_f32_16x16x32_bf16 v[80:83], v[178:181], v[202:205], v[80:83]
	v_mfma_f32_16x16x32_bf16 v[68:71], v[170:173], v[210:213], v[68:71]
	v_mfma_f32_16x16x32_bf16 v[64:67], v[178:181], v[210:213], v[64:67]
	s_barrier
	s_add_i32 s18, s51, s23
	v_lshl_add_u64 v[214:215], v[214:215], 0, s[6:7]
	s_mov_b32 m0, s18
	ds_read_b128 v[182:185], v169 offset:49152
	ds_read_b128 v[186:189], v169 offset:50176
	ds_read_b128 v[190:193], v169 offset:51200
	ds_read_b128 v[194:197], v169 offset:52224
	ds_read_b128 v[198:201], v169 offset:53248
	ds_read_b128 v[202:205], v169 offset:54272
	ds_read_b128 v[206:209], v169 offset:55296
	ds_read_b128 v[210:213], v169 offset:56320
	global_load_lds_dwordx4 v[214:215], off
	s_add_i32 m0, s18, 0x2000
	s_add_u32 s16, s16, 0xb0080
	v_lshl_add_u64 v[214:215], v[216:217], 0, s[6:7]
	s_addc_u32 s17, s17, 0
	s_add_i32 s18, s52, s23
	global_load_lds_dwordx4 v[214:215], off
	v_lshl_add_u64 v[214:215], s[16:17], 0, v[130:131]
	s_mov_b32 m0, s18
	s_nop 0
	global_load_lds_dwordx4 v[214:215], off
	v_lshl_add_u64 v[214:215], s[16:17], 0, v[134:135]
	s_add_i32 m0, s18, 0x2000
	s_nop 0
	global_load_lds_dwordx4 v[214:215], off
	v_lshl_add_u64 v[214:215], v[218:219], 0, s[6:7]
	s_mov_b32 m0, s35
	s_nop 0
	global_load_lds_dwordx4 v[214:215], off
	v_lshl_add_u64 v[214:215], v[220:221], 0, s[6:7]
	s_mov_b32 m0, s39
	s_nop 0
	global_load_lds_dwordx4 v[214:215], off
	s_waitcnt vmcnt(8)
	s_waitcnt lgkmcnt(0)
	s_barrier
	s_waitcnt lgkmcnt(0)
	v_mfma_f32_16x16x32_bf16 v[60:63], v[144:147], v[182:185], v[60:63]
	v_mfma_f32_16x16x32_bf16 v[56:59], v[152:155], v[182:185], v[56:59]
	v_mfma_f32_16x16x32_bf16 v[44:47], v[144:147], v[190:193], v[44:47]
	v_mfma_f32_16x16x32_bf16 v[40:43], v[152:155], v[190:193], v[40:43]
	v_mfma_f32_16x16x32_bf16 v[28:31], v[144:147], v[198:201], v[28:31]
	v_mfma_f32_16x16x32_bf16 v[24:27], v[152:155], v[198:201], v[24:27]
	v_mfma_f32_16x16x32_bf16 v[12:15], v[144:147], v[206:209], v[12:15]
	v_mfma_f32_16x16x32_bf16 v[8:11], v[152:155], v[206:209], v[8:11]
	v_mfma_f32_16x16x32_bf16 v[60:63], v[148:151], v[186:189], v[60:63]
	v_mfma_f32_16x16x32_bf16 v[56:59], v[156:159], v[186:189], v[56:59]
	v_mfma_f32_16x16x32_bf16 v[44:47], v[148:151], v[194:197], v[44:47]
	v_mfma_f32_16x16x32_bf16 v[40:43], v[156:159], v[194:197], v[40:43]
	v_mfma_f32_16x16x32_bf16 v[28:31], v[148:151], v[202:205], v[28:31]
	v_mfma_f32_16x16x32_bf16 v[24:27], v[156:159], v[202:205], v[24:27]
	v_mfma_f32_16x16x32_bf16 v[12:15], v[148:151], v[210:213], v[12:15]
	v_mfma_f32_16x16x32_bf16 v[8:11], v[156:159], v[210:213], v[8:11]
	v_mfma_f32_16x16x32_bf16 v[52:55], v[160:163], v[182:185], v[52:55]
	v_mfma_f32_16x16x32_bf16 v[48:51], v[174:177], v[182:185], v[48:51]
	v_mfma_f32_16x16x32_bf16 v[36:39], v[160:163], v[190:193], v[36:39]
	v_mfma_f32_16x16x32_bf16 v[32:35], v[174:177], v[190:193], v[32:35]
	v_mfma_f32_16x16x32_bf16 v[20:23], v[160:163], v[198:201], v[20:23]
	v_mfma_f32_16x16x32_bf16 v[16:19], v[174:177], v[198:201], v[16:19]
	v_mfma_f32_16x16x32_bf16 v[4:7], v[160:163], v[206:209], v[4:7]
	v_mfma_f32_16x16x32_bf16 v[0:3], v[174:177], v[206:209], v[0:3]
	v_mfma_f32_16x16x32_bf16 v[52:55], v[170:173], v[186:189], v[52:55]
	v_mfma_f32_16x16x32_bf16 v[48:51], v[178:181], v[186:189], v[48:51]
	v_mfma_f32_16x16x32_bf16 v[36:39], v[170:173], v[194:197], v[36:39]
	v_mfma_f32_16x16x32_bf16 v[32:35], v[178:181], v[194:197], v[32:35]
	v_mfma_f32_16x16x32_bf16 v[20:23], v[170:173], v[202:205], v[20:23]
	v_mfma_f32_16x16x32_bf16 v[16:19], v[178:181], v[202:205], v[16:19]
	v_mfma_f32_16x16x32_bf16 v[4:7], v[170:173], v[210:213], v[4:7]
	v_mfma_f32_16x16x32_bf16 v[0:3], v[178:181], v[210:213], v[0:3]
	s_barrier
	s_add_i32 s50, s50, 2
	s_add_u32 s14, s14, 0x100
	s_addc_u32 s15, s15, 0
	s_add_u32 s48, s48, 0x100
	s_addc_u32 s49, s49, 0
	s_cmp_gt_u32 s50, 41
	s_cbranch_scc0 .LBB0_1786
	s_and_b64 vcc, exec, s[8:9]
	s_cbranch_vccz .LBB0_1789
	s_barrier
